# GEMM K-loop DMA addressing via SGPR base plus 32-bit lane offsets (ffn_up, w_in): removes 23 VALU per wave per K-step
# speedup vs baseline: 1.0437x; 1.0026x over previous
; DI int tid_() { int t = threadIdx.x; asm volatile("" : "+v"(t)); return t; }
;     ...
;   const int tid = tid_(), w = tid >> 6, l = tid & 63, r16 = l & 15, q4 = l >> 4;
;   const int wm = w >> 2, wn = w & 3;
;   f32x4 acc[MT][4];
; #pragma unroll
;   for (int a = 0; a < MT; ++a)
; #pragma unroll
;     for (int b = 0; b < 4; ++b) { acc[a][b][0] = 0.f; acc[a][b][1] = 0.f; acc[a][b][2] = 0.f; acc[a][b][3] = 0.f; }
;   const int srow = tid >> 3, slog = (tid & 7) ^ ((tid >> 4) & 7);
;   const bf16_t* Ag = A + (size_t)(m0 + srow) * lda + slog * 8;
;   const bf16_t* Bg0 = B + (size_t)min(n0 + srow, N - 1) * ldb + slog * 8;
;   const bf16_t* Bg1 = B + (size_t)min(n0 + srow + 64, N - 1) * ldb + slog * 8;
;   const bf16_t* Bg2 = B + (size_t)min(n0 + srow + 128, N - 1) * ldb + slog * 8;
;   const bf16_t* Bg3 = B + (size_t)min(n0 + srow + 192, N - 1) * ldb + slog * 8;
;   char* wbase = smem + w * 1024;
;     ...
;   const int nk = K >> 6;
;   __syncthreads();
;   STAGE_TILE(0, 0)
;   asm volatile("s_waitcnt vmcnt(0)" ::: "memory");
;   __syncthreads();
;   const int swz = r16 >> 1;
.LBB0_74:
	v_mov_b32_e32 v16, v0
	s_lshl_b32 s38, s40, 8
	v_readlane_b32 s52, v253, 40
	v_ashrrev_i32_e32 v4, 3, v16
	v_lshrrev_b32_e32 v17, 4, v16
	v_add_u32_e32 v2, s38, v4
	v_xor_b32_e32 v5, v17, v16
	v_ashrrev_i32_e32 v3, 31, v2
	v_ashrrev_i32_e32 v14, 6, v16
	v_lshlrev_b64 v[2:3], 11, v[2:3]
	v_readlane_b32 s53, v253, 41
	v_lshlrev_b32_e32 v5, 4, v5
	s_lshl_b32 s39, s39, 8
	v_lshl_add_u64 v[2:3], s[52:53], 0, v[2:3]
	v_and_b32_e32 v190, 0x70, v5
	v_lshl_add_u32 v145, v14, 10, 0
	v_lshl_add_u64 v[130:131], v[2:3], 0, v[190:191]
	v_add_u32_e32 v2, s39, v4
	v_readfirstlane_b32 s16, v145
	v_add_u32_e32 v3, 0x2000, v145
	v_min_i32_e32 v4, 0x15ff, v2
	v_min_i32_e32 v8, 0x15bf, v2
	s_mov_b64 s[40:41], 0x20000
	s_mov_b32 m0, s16
	v_readfirstlane_b32 s16, v3
	v_add_u32_e32 v3, 0x4000, v145
	v_and_b32_e32 v143, 3, v14
	v_ashrrev_i32_e32 v5, 31, v4
	v_ashrrev_i32_e32 v9, 31, v8
	v_min_i32_e32 v10, 0x157f, v2
	s_mov_b64 s[42:43], 0x40000
	s_barrier
	global_load_lds_dwordx4 v[130:131], off
	v_lshl_add_u64 v[14:15], v[130:131], 0, s[40:41]
	s_mov_b32 m0, s16
	v_readfirstlane_b32 s16, v3
	v_add_u32_e32 v3, 0x6000, v145
	v_lshlrev_b64 v[4:5], 11, v[4:5]
	v_lshlrev_b64 v[8:9], 11, v[8:9]
	v_ashrrev_i32_e32 v11, 31, v10
	v_min_i32_e32 v12, 0x153f, v2
	s_mov_b64 s[44:45], 0x60000
	global_load_lds_dwordx4 v[14:15], off
	v_lshl_add_u64 v[14:15], v[130:131], 0, s[42:43]
	s_mov_b32 m0, s16
	v_readfirstlane_b32 s16, v3
	v_add_u32_e32 v3, 0x8000, v145
	v_lshl_add_u64 v[6:7], s[2:3], 0, v[4:5]
	v_lshl_add_u64 v[8:9], s[2:3], 0, v[8:9]
	v_lshlrev_b64 v[10:11], 11, v[10:11]
	v_ashrrev_i32_e32 v13, 31, v12
	global_load_lds_dwordx4 v[14:15], off
	v_lshl_add_u64 v[14:15], v[130:131], 0, s[44:45]
	s_mov_b32 m0, s16
	v_readfirstlane_b32 s16, v3
	v_add_u32_e32 v3, 0xa000, v145
	v_lshl_add_u64 v[6:7], v[6:7], 0, v[190:191]
	v_lshl_add_u64 v[8:9], v[8:9], 0, v[190:191]
	v_lshl_add_u64 v[10:11], s[2:3], 0, v[10:11]
	v_lshlrev_b64 v[12:13], 11, v[12:13]
	global_load_lds_dwordx4 v[14:15], off
	s_mov_b32 m0, s16
	v_readfirstlane_b32 s16, v3
	v_add_u32_e32 v3, 0xc000, v145
	v_lshl_add_u64 v[8:9], v[8:9], 0, s[40:41]
	v_lshl_add_u64 v[10:11], v[10:11], 0, v[190:191]
	v_lshl_add_u64 v[12:13], s[2:3], 0, v[12:13]
	global_load_lds_dwordx4 v[6:7], off
	s_mov_b32 m0, s16
	v_readfirstlane_b32 s16, v3
	v_add_u32_e32 v3, 0xe000, v145
	v_lshl_add_u64 v[10:11], v[10:11], 0, s[42:43]
	v_lshl_add_u64 v[12:13], v[12:13], 0, v[190:191]
	global_load_lds_dwordx4 v[8:9], off
	s_mov_b32 m0, s16
	v_readfirstlane_b32 s16, v3
	v_lshl_add_u64 v[12:13], v[12:13], 0, s[44:45]
	global_load_lds_dwordx4 v[10:11], off
	s_mov_b32 m0, s16
	v_and_b32_e32 v142, 15, v16
	global_load_lds_dwordx4 v[12:13], off
	v_ashrrev_i32_e32 v141, 8, v16
	v_bfe_u32 v140, v16, 4, 2
	v_bfe_u32 v3, v16, 1, 3
	v_lshlrev_b32_e32 v6, 7, v142
	v_lshl_or_b32 v148, v141, 14, v6
	v_lshl_or_b32 v147, v143, 13, v6
	v_bitop3_b32 v6, v17, v3, 3 bitop3:0x6c
	v_bitop3_b32 v3, v140, v3, 4 bitop3:0x36
	v_lshlrev_b32_e32 v144, 4, v3
	v_ashrrev_i32_e32 v3, 31, v2
	s_mov_b64 s[16:17], 0x153f
	v_cmp_gt_i64_e32 vcc, s[16:17], v[2:3]
	v_lshlrev_b32_e32 v146, 4, v6
	v_bitop3_b32 v8, v17, 7, v16 bitop3:0x48
	v_cndmask_b32_e32 v7, 0, v3, vcc
	v_cndmask_b32_e32 v6, v248, v2, vcc
	v_lshlrev_b64 v[6:7], 11, v[6:7]
	v_lshlrev_b32_e32 v8, 4, v8
	s_mov_b64 s[16:17], 0x157f
	v_or_b32_e32 v6, v6, v8
	v_cmp_gt_i64_e32 vcc, s[16:17], v[2:3]
	s_mov_b64 s[16:17], 0x15bf
	v_lshl_add_u64 v[132:133], s[8:9], 0, v[6:7]
	v_cndmask_b32_e32 v7, 0, v3, vcc
	v_cndmask_b32_e32 v6, v249, v2, vcc
	v_cmp_gt_i64_e32 vcc, s[16:17], v[2:3]
	s_waitcnt vmcnt(0)
	v_lshlrev_b64 v[6:7], 11, v[6:7]
	v_or_b32_e32 v6, v6, v8
	v_cndmask_b32_e32 v3, 0, v3, vcc
	v_cndmask_b32_e32 v2, v247, v2, vcc
	v_lshlrev_b64 v[2:3], 11, v[2:3]
	v_or_b32_e32 v2, v2, v8
	v_lshl_add_u64 v[136:137], s[12:13], 0, v[2:3]
	v_or_b32_e32 v4, v4, v8
	v_mov_b32_e32 v2, 0
	s_mov_b32 s40, 0
	v_lshl_add_u64 v[134:135], s[10:11], 0, v[6:7]
	v_lshl_add_u64 v[138:139], s[14:15], 0, v[4:5]
	s_mov_b64 s[16:17], 0
	v_mov_b32_e32 v3, v2
	v_mov_b32_e32 v4, v2
	v_mov_b32_e32 v5, v2
	v_mov_b32_e32 v6, v2
	v_mov_b32_e32 v7, v2
	v_mov_b32_e32 v8, v2
	v_mov_b32_e32 v9, v2
	v_mov_b32_e32 v10, v2
	v_mov_b32_e32 v11, v2
	v_mov_b32_e32 v12, v2
	v_mov_b32_e32 v13, v2
	v_mov_b32_e32 v14, v2
	v_mov_b32_e32 v15, v2
	v_mov_b32_e32 v16, v2
	v_mov_b32_e32 v17, v2
	v_mov_b32_e32 v18, v2
	v_mov_b32_e32 v19, v2
	v_mov_b32_e32 v20, v2
	v_mov_b32_e32 v21, v2
	v_mov_b32_e32 v22, v2
	v_mov_b32_e32 v23, v2
	v_mov_b32_e32 v24, v2
	v_mov_b32_e32 v25, v2
	v_mov_b32_e32 v26, v2
	v_mov_b32_e32 v27, v2
	v_mov_b32_e32 v28, v2
	v_mov_b32_e32 v29, v2
	v_mov_b32_e32 v30, v2
	v_mov_b32_e32 v31, v2
	v_mov_b32_e32 v32, v2
	v_mov_b32_e32 v33, v2
	v_mov_b32_e32 v34, v2
	v_mov_b32_e32 v35, v2
	v_mov_b32_e32 v36, v2
	v_mov_b32_e32 v37, v2
	v_mov_b32_e32 v38, v2
	v_mov_b32_e32 v39, v2
	v_mov_b32_e32 v40, v2
	v_mov_b32_e32 v41, v2
	v_mov_b32_e32 v42, v2
	v_mov_b32_e32 v43, v2
	v_mov_b32_e32 v44, v2
	v_mov_b32_e32 v45, v2
	v_mov_b32_e32 v46, v2
	v_mov_b32_e32 v47, v2
	v_mov_b32_e32 v48, v2
	v_mov_b32_e32 v49, v2
	v_mov_b32_e32 v50, v2
	v_mov_b32_e32 v51, v2
	v_mov_b32_e32 v52, v2
	v_mov_b32_e32 v53, v2
	v_mov_b32_e32 v54, v2
	v_mov_b32_e32 v55, v2
	v_mov_b32_e32 v56, v2
	v_mov_b32_e32 v57, v2
	v_mov_b32_e32 v58, v2
	v_mov_b32_e32 v59, v2
	v_mov_b32_e32 v60, v2
	v_mov_b32_e32 v61, v2
	v_mov_b32_e32 v62, v2
	v_mov_b32_e32 v63, v2
	v_mov_b32_e32 v64, v2
	v_mov_b32_e32 v65, v2
	v_mov_b32_e32 v66, v2
	v_mov_b32_e32 v67, v2
	v_mov_b32_e32 v68, v2
	v_mov_b32_e32 v69, v2
	v_mov_b32_e32 v70, v2
	v_mov_b32_e32 v71, v2
	v_mov_b32_e32 v72, v2
	v_mov_b32_e32 v73, v2
	v_mov_b32_e32 v74, v2
	v_mov_b32_e32 v75, v2
	v_mov_b32_e32 v76, v2
	v_mov_b32_e32 v77, v2
	v_mov_b32_e32 v78, v2
	v_mov_b32_e32 v79, v2
	v_mov_b32_e32 v80, v2
	v_mov_b32_e32 v81, v2
	s_waitcnt vmcnt(0)
; #define MFMA16(a, b, c) __builtin_amdgcn_mfma_f32_16x16x32_bf16((a), (b), (c), 0, 0, 0)
;     ...
;   for (int kt = 0; kt < nk; ++kt) {
;     const int buf = kt & 1;
;     const char* cA = smem + buf * STAGE + (wm * 32 * MI + r16) * 128;
;     const char* cB = smem + buf * STAGE + 32768 + (wn * 64 + r16) * 128;
; #pragma unroll
;     for (int k2 = 0; k2 < 2; ++k2) {
;       if (k2 == 1 && kt + 1 < nk) STAGE_TILE(buf ^ 1, (kt + 1) * 64)
;       const int po = ((4 * k2 + q4) ^ swz) * 16;
;       bf16x8 bf[4];
; #pragma unroll
;       for (int nt = 0; nt < 4; ++nt) bf[nt] = *(const bf16x8*)(cB + nt * 16 * 128 + po);
;       bf16x8 afc = *(const bf16x8*)(cA + po);
; #pragma unroll
;       for (int a = 0; a < MT; ++a) {
;         bf16x8 afn = afc;
;         if (a + 1 < MT) afn = *(const bf16x8*)(cA + (a + 1) * 16 * 128 + po);
;         __builtin_amdgcn_sched_barrier(0);
; #pragma unroll
;         for (int nt = 0; nt < 4; ++nt) acc[a][nt] = MFMA16(bf[nt], afc, acc[a][nt]);
;         __builtin_amdgcn_sched_barrier(0);
;         afc = afn;
;       }
;     }
;     asm volatile("s_waitcnt vmcnt(0)" ::: "memory");
;     __syncthreads();
	v_mov_b32_e32 v82, v2
	v_mov_b32_e32 v83, v2
	v_mov_b32_e32 v84, v2
	v_mov_b32_e32 v85, v2
	v_mov_b32_e32 v86, v2
	v_mov_b32_e32 v87, v2
	v_mov_b32_e32 v88, v2
	v_mov_b32_e32 v89, v2
	v_mov_b32_e32 v90, v2
	v_mov_b32_e32 v91, v2
	v_mov_b32_e32 v92, v2
	v_mov_b32_e32 v93, v2
	v_mov_b32_e32 v94, v2
	v_mov_b32_e32 v95, v2
	v_mov_b32_e32 v96, v2
	v_mov_b32_e32 v97, v2
	v_mov_b32_e32 v98, v2
	v_mov_b32_e32 v99, v2
	v_mov_b32_e32 v100, v2
	v_mov_b32_e32 v101, v2
	v_mov_b32_e32 v102, v2
	v_mov_b32_e32 v103, v2
	v_mov_b32_e32 v104, v2
	v_mov_b32_e32 v105, v2
	v_mov_b32_e32 v106, v2
	v_mov_b32_e32 v107, v2
	v_mov_b32_e32 v108, v2
	v_mov_b32_e32 v109, v2
	v_mov_b32_e32 v110, v2
	v_mov_b32_e32 v111, v2
	v_mov_b32_e32 v112, v2
	v_mov_b32_e32 v113, v2
	v_mov_b32_e32 v114, v2
	v_mov_b32_e32 v115, v2
	v_mov_b32_e32 v116, v2
	v_mov_b32_e32 v117, v2
	v_mov_b32_e32 v118, v2
	v_mov_b32_e32 v119, v2
	v_mov_b32_e32 v120, v2
	v_mov_b32_e32 v121, v2
	v_mov_b32_e32 v122, v2
	v_mov_b32_e32 v123, v2
	v_mov_b32_e32 v124, v2
	v_mov_b32_e32 v125, v2
	v_mov_b32_e32 v126, v2
	v_mov_b32_e32 v127, v2
	v_mov_b32_e32 v128, v2
	v_mov_b32_e32 v129, v2
	v_readlane_b32 s54, v253, 42
	v_readlane_b32 s55, v253, 43
	v_readlane_b32 s56, v253, 44
	v_readlane_b32 s57, v253, 45
	v_readlane_b32 s58, v253, 46
	v_readlane_b32 s59, v253, 47
	v_readlane_b32 s60, v253, 48
	v_readlane_b32 s61, v253, 49
	v_readlane_b32 s62, v253, 50
	v_readlane_b32 s63, v253, 51
	v_readlane_b32 s64, v253, 52
	v_readlane_b32 s65, v253, 53
	v_readlane_b32 s66, v253, 54
	v_readlane_b32 s67, v253, 55
	s_waitcnt vmcnt(0) lgkmcnt(0)
	s_barrier
	v_readfirstlane_b32 s100, v138
	v_readfirstlane_b32 s101, v139
	s_nop 0
	s_sub_u32 s100, s100, 0x80
	s_subb_u32 s101, s101, 0
	v_add_u32_e32 v174, s24, v130
	v_subrev_u32_e32 v174, s100, v174
	v_add_u32_e32 v175, s84, v130
	v_subrev_u32_e32 v175, s100, v175
	v_add_u32_e32 v176, s28, v130
	v_subrev_u32_e32 v176, s100, v176
	v_add_u32_e32 v177, s18, v130
	v_subrev_u32_e32 v177, s100, v177
	v_subrev_u32_e32 v178, s100, v138
	v_subrev_u32_e32 v179, s100, v136
	v_subrev_u32_e32 v180, s100, v134
	v_subrev_u32_e32 v181, s100, v132
.LBB0_75:
	s_and_b32 s41, s40, 0x10000
	s_add_i32 s42, s41, 0
	v_add_u32_e32 v190, s42, v147
	v_add_u32_e32 v162, v190, v146
	v_add_u32_e32 v149, s42, v148
	ds_read_b128 v[150:153], v162 offset:32768
	ds_read_b128 v[154:157], v162 offset:34816
	ds_read_b128 v[158:161], v162 offset:36864
	ds_read_b128 v[162:165], v162 offset:38912
	v_add_u32_e32 v202, v149, v146
	ds_read_b128 v[166:169], v202
	ds_read_b128 v[170:173], v202 offset:2048
	s_xor_b32 s41, s41, 0x10000
	s_waitcnt lgkmcnt(1)
	v_mfma_f32_16x16x32_bf16 v[126:129], v[150:153], v[166:169], v[126:129]
	v_mfma_f32_16x16x32_bf16 v[122:125], v[154:157], v[166:169], v[122:125]
	v_mfma_f32_16x16x32_bf16 v[118:121], v[158:161], v[166:169], v[118:121]
	v_mfma_f32_16x16x32_bf16 v[114:117], v[162:165], v[166:169], v[114:117]
	ds_read_b128 v[166:169], v202 offset:4096
	s_waitcnt lgkmcnt(1)
	v_mfma_f32_16x16x32_bf16 v[110:113], v[150:153], v[170:173], v[110:113]
	v_mfma_f32_16x16x32_bf16 v[106:109], v[154:157], v[170:173], v[106:109]
	v_mfma_f32_16x16x32_bf16 v[102:105], v[158:161], v[170:173], v[102:105]
	v_mfma_f32_16x16x32_bf16 v[98:101], v[162:165], v[170:173], v[98:101]
	ds_read_b128 v[170:173], v202 offset:6144
	s_waitcnt lgkmcnt(1)
	v_mfma_f32_16x16x32_bf16 v[94:97], v[150:153], v[166:169], v[94:97]
	v_mfma_f32_16x16x32_bf16 v[90:93], v[154:157], v[166:169], v[90:93]
	v_mfma_f32_16x16x32_bf16 v[86:89], v[158:161], v[166:169], v[86:89]
	v_mfma_f32_16x16x32_bf16 v[82:85], v[162:165], v[166:169], v[82:85]
	ds_read_b128 v[166:169], v202 offset:8192
	s_waitcnt lgkmcnt(1)
	v_mfma_f32_16x16x32_bf16 v[78:81], v[150:153], v[170:173], v[78:81]
	v_mfma_f32_16x16x32_bf16 v[74:77], v[154:157], v[170:173], v[74:77]
	v_mfma_f32_16x16x32_bf16 v[70:73], v[158:161], v[170:173], v[70:73]
	v_mfma_f32_16x16x32_bf16 v[66:69], v[162:165], v[170:173], v[66:69]
	ds_read_b128 v[170:173], v202 offset:10240
	s_waitcnt lgkmcnt(1)
	v_mfma_f32_16x16x32_bf16 v[62:65], v[150:153], v[166:169], v[62:65]
	v_mfma_f32_16x16x32_bf16 v[58:61], v[154:157], v[166:169], v[58:61]
	v_mfma_f32_16x16x32_bf16 v[54:57], v[158:161], v[166:169], v[54:57]
	v_mfma_f32_16x16x32_bf16 v[50:53], v[162:165], v[166:169], v[50:53]
	ds_read_b128 v[166:169], v202 offset:12288
	s_waitcnt lgkmcnt(1)
	v_mfma_f32_16x16x32_bf16 v[46:49], v[150:153], v[170:173], v[46:49]
	v_mfma_f32_16x16x32_bf16 v[42:45], v[154:157], v[170:173], v[42:45]
	v_mfma_f32_16x16x32_bf16 v[38:41], v[158:161], v[170:173], v[38:41]
	v_mfma_f32_16x16x32_bf16 v[34:37], v[162:165], v[170:173], v[34:37]
	ds_read_b128 v[170:173], v202 offset:14336
	s_waitcnt lgkmcnt(1)
	v_mfma_f32_16x16x32_bf16 v[30:33], v[150:153], v[166:169], v[30:33]
	v_mfma_f32_16x16x32_bf16 v[26:29], v[154:157], v[166:169], v[26:29]
	v_mfma_f32_16x16x32_bf16 v[22:25], v[158:161], v[166:169], v[22:25]
	v_mfma_f32_16x16x32_bf16 v[18:21], v[162:165], v[166:169], v[18:21]
	s_waitcnt lgkmcnt(0)
	v_mfma_f32_16x16x32_bf16 v[14:17], v[150:153], v[170:173], v[14:17]
	v_mfma_f32_16x16x32_bf16 v[10:13], v[154:157], v[170:173], v[10:13]
	v_mfma_f32_16x16x32_bf16 v[6:9], v[158:161], v[170:173], v[6:9]
	v_mfma_f32_16x16x32_bf16 v[2:5], v[162:165], v[170:173], v[2:5]
	v_readfirstlane_b32 s42, v145
	s_nop 0
	s_add_u32 s42, s42, s41
	s_add_u32 m0, s42, 0x0
	s_nop 0
	global_load_lds_dwordx4 v174, s[100:101]
	s_add_u32 m0, s42, 0x2000
	s_nop 0
	global_load_lds_dwordx4 v175, s[100:101]
	s_add_u32 m0, s42, 0x4000
	s_nop 0
	global_load_lds_dwordx4 v176, s[100:101]
	s_add_u32 m0, s42, 0x6000
	s_nop 0
	global_load_lds_dwordx4 v177, s[100:101]
	s_add_u32 m0, s42, 0x8000
	s_nop 0
	global_load_lds_dwordx4 v178, s[100:101]
	s_add_u32 m0, s42, 0xa000
	s_nop 0
	global_load_lds_dwordx4 v179, s[100:101]
	s_add_u32 m0, s42, 0xc000
	s_nop 0
	global_load_lds_dwordx4 v180, s[100:101]
	s_add_u32 m0, s42, 0xe000
	s_nop 0
	global_load_lds_dwordx4 v181, s[100:101]
	v_add_u32_e32 v162, v190, v144
	ds_read_b128 v[150:153], v162 offset:32768
	ds_read_b128 v[154:157], v162 offset:34816
	ds_read_b128 v[158:161], v162 offset:36864
	ds_read_b128 v[162:165], v162 offset:38912
	v_add_u32_e32 v149, v149, v144
	ds_read_b128 v[166:169], v149
	ds_read_b128 v[170:173], v149 offset:2048
	s_waitcnt lgkmcnt(0)
; #define MFMA16(a, b, c) __builtin_amdgcn_mfma_f32_16x16x32_bf16((a), (b), (c), 0, 0, 0)
;     ...
;   for (int kt = 0; kt < nk; ++kt) {
;     const int buf = kt & 1;
;     const char* cA = smem + buf * STAGE + (wm * 32 * MI + r16) * 128;
;     const char* cB = smem + buf * STAGE + 32768 + (wn * 64 + r16) * 128;
; #pragma unroll
;     for (int k2 = 0; k2 < 2; ++k2) {
;       if (k2 == 1 && kt + 1 < nk) STAGE_TILE(buf ^ 1, (kt + 1) * 64)
;       const int po = ((4 * k2 + q4) ^ swz) * 16;
;       bf16x8 bf[4];
; #pragma unroll
;       for (int nt = 0; nt < 4; ++nt) bf[nt] = *(const bf16x8*)(cB + nt * 16 * 128 + po);
;       bf16x8 afc = *(const bf16x8*)(cA + po);
; #pragma unroll
;       for (int a = 0; a < MT; ++a) {
;         bf16x8 afn = afc;
;         if (a + 1 < MT) afn = *(const bf16x8*)(cA + (a + 1) * 16 * 128 + po);
;         __builtin_amdgcn_sched_barrier(0);
; #pragma unroll
;         for (int nt = 0; nt < 4; ++nt) acc[a][nt] = MFMA16(bf[nt], afc, acc[a][nt]);
;         __builtin_amdgcn_sched_barrier(0);
;         afc = afn;
;       }
;     }
;     asm volatile("s_waitcnt vmcnt(0)" ::: "memory");
;     __syncthreads();
;   }
	v_mfma_f32_16x16x32_bf16 v[126:129], v[150:153], v[166:169], v[126:129]
	v_mfma_f32_16x16x32_bf16 v[122:125], v[154:157], v[166:169], v[122:125]
	v_mfma_f32_16x16x32_bf16 v[118:121], v[158:161], v[166:169], v[118:121]
	v_mfma_f32_16x16x32_bf16 v[114:117], v[162:165], v[166:169], v[114:117]
	ds_read_b128 v[166:169], v149 offset:4096
	v_mfma_f32_16x16x32_bf16 v[110:113], v[150:153], v[170:173], v[110:113]
	v_mfma_f32_16x16x32_bf16 v[106:109], v[154:157], v[170:173], v[106:109]
	v_mfma_f32_16x16x32_bf16 v[102:105], v[158:161], v[170:173], v[102:105]
	v_mfma_f32_16x16x32_bf16 v[98:101], v[162:165], v[170:173], v[98:101]
	ds_read_b128 v[170:173], v149 offset:6144
	s_waitcnt lgkmcnt(0)
	v_mfma_f32_16x16x32_bf16 v[94:97], v[150:153], v[166:169], v[94:97]
	v_mfma_f32_16x16x32_bf16 v[90:93], v[154:157], v[166:169], v[90:93]
	v_mfma_f32_16x16x32_bf16 v[86:89], v[158:161], v[166:169], v[86:89]
	v_mfma_f32_16x16x32_bf16 v[82:85], v[162:165], v[166:169], v[82:85]
	ds_read_b128 v[166:169], v149 offset:8192
	v_mfma_f32_16x16x32_bf16 v[78:81], v[150:153], v[170:173], v[78:81]
	v_mfma_f32_16x16x32_bf16 v[74:77], v[154:157], v[170:173], v[74:77]
	v_mfma_f32_16x16x32_bf16 v[70:73], v[158:161], v[170:173], v[70:73]
	v_mfma_f32_16x16x32_bf16 v[66:69], v[162:165], v[170:173], v[66:69]
	ds_read_b128 v[170:173], v149 offset:10240
	s_waitcnt lgkmcnt(0)
	v_mfma_f32_16x16x32_bf16 v[62:65], v[150:153], v[166:169], v[62:65]
	v_mfma_f32_16x16x32_bf16 v[58:61], v[154:157], v[166:169], v[58:61]
	v_mfma_f32_16x16x32_bf16 v[54:57], v[158:161], v[166:169], v[54:57]
	v_mfma_f32_16x16x32_bf16 v[50:53], v[162:165], v[166:169], v[50:53]
	ds_read_b128 v[166:169], v149 offset:12288
	v_mfma_f32_16x16x32_bf16 v[46:49], v[150:153], v[170:173], v[46:49]
	v_mfma_f32_16x16x32_bf16 v[42:45], v[154:157], v[170:173], v[42:45]
	v_mfma_f32_16x16x32_bf16 v[38:41], v[158:161], v[170:173], v[38:41]
	v_mfma_f32_16x16x32_bf16 v[34:37], v[162:165], v[170:173], v[34:37]
	ds_read_b128 v[170:173], v149 offset:14336
	s_waitcnt lgkmcnt(0)
	v_mfma_f32_16x16x32_bf16 v[30:33], v[150:153], v[166:169], v[30:33]
	v_mfma_f32_16x16x32_bf16 v[26:29], v[154:157], v[166:169], v[26:29]
	v_mfma_f32_16x16x32_bf16 v[22:25], v[158:161], v[166:169], v[22:25]
	v_mfma_f32_16x16x32_bf16 v[18:21], v[162:165], v[166:169], v[18:21]
	v_mfma_f32_16x16x32_bf16 v[14:17], v[150:153], v[170:173], v[14:17]
	v_mfma_f32_16x16x32_bf16 v[10:13], v[154:157], v[170:173], v[10:13]
	v_mfma_f32_16x16x32_bf16 v[6:9], v[158:161], v[170:173], v[6:9]
	v_mfma_f32_16x16x32_bf16 v[2:5], v[162:165], v[170:173], v[2:5]
	s_waitcnt vmcnt(0)
	s_add_u32 s100, s100, 0x80
	s_addc_u32 s101, s101, 0
	s_add_u32 s16, s16, 0x80
	s_addc_u32 s17, s17, 0
	s_add_i32 s40, s40, 0x10000
	s_cmpk_lg_i32 s16, 0x780
	s_waitcnt vmcnt(0)
	s_barrier
	s_cbranch_scc1 .LBB0_75
	s_add_i32 s16, 0, 0x10000
	v_add_u32_e32 v138, s16, v148
	v_readlane_b32 s16, v254, 18
	s_nop 1
	v_add_u32_e32 v139, s16, v147
	v_add_u32_e32 v145, v139, v146
	ds_read_b128 v[130:133], v145
	ds_read_b128 v[134:137], v145 offset:2048
	ds_read_b128 v[148:151], v145 offset:4096
	ds_read_b128 v[152:155], v145 offset:6144
	v_add_u32_e32 v145, v138, v146
	ds_read_b128 v[156:159], v145
	ds_read_b128 v[160:163], v145 offset:2048
	s_waitcnt lgkmcnt(1)
	v_mfma_f32_16x16x32_bf16 v[126:129], v[130:133], v[156:159], v[126:129]
	v_mfma_f32_16x16x32_bf16 v[122:125], v[134:137], v[156:159], v[122:125]
	v_mfma_f32_16x16x32_bf16 v[118:121], v[148:151], v[156:159], v[118:121]
	v_mfma_f32_16x16x32_bf16 v[114:117], v[152:155], v[156:159], v[114:117]
	ds_read_b128 v[156:159], v145 offset:4096
	s_waitcnt lgkmcnt(1)
	v_mfma_f32_16x16x32_bf16 v[110:113], v[130:133], v[160:163], v[110:113]
	v_mfma_f32_16x16x32_bf16 v[106:109], v[134:137], v[160:163], v[106:109]
	v_mfma_f32_16x16x32_bf16 v[102:105], v[148:151], v[160:163], v[102:105]
	v_mfma_f32_16x16x32_bf16 v[98:101], v[152:155], v[160:163], v[98:101]
	ds_read_b128 v[160:163], v145 offset:6144
	s_waitcnt lgkmcnt(1)
	v_mfma_f32_16x16x32_bf16 v[94:97], v[130:133], v[156:159], v[94:97]
	v_mfma_f32_16x16x32_bf16 v[90:93], v[134:137], v[156:159], v[90:93]
	v_mfma_f32_16x16x32_bf16 v[86:89], v[148:151], v[156:159], v[86:89]
	v_mfma_f32_16x16x32_bf16 v[82:85], v[152:155], v[156:159], v[82:85]
	ds_read_b128 v[156:159], v145 offset:8192
	s_waitcnt lgkmcnt(1)
	v_mfma_f32_16x16x32_bf16 v[78:81], v[130:133], v[160:163], v[78:81]
	v_mfma_f32_16x16x32_bf16 v[74:77], v[134:137], v[160:163], v[74:77]
	v_mfma_f32_16x16x32_bf16 v[70:73], v[148:151], v[160:163], v[70:73]
	v_mfma_f32_16x16x32_bf16 v[66:69], v[152:155], v[160:163], v[66:69]
	ds_read_b128 v[160:163], v145 offset:10240
	s_waitcnt lgkmcnt(1)
	v_mfma_f32_16x16x32_bf16 v[62:65], v[130:133], v[156:159], v[62:65]
	v_mfma_f32_16x16x32_bf16 v[58:61], v[134:137], v[156:159], v[58:61]
	v_mfma_f32_16x16x32_bf16 v[54:57], v[148:151], v[156:159], v[54:57]
	v_mfma_f32_16x16x32_bf16 v[50:53], v[152:155], v[156:159], v[50:53]
	ds_read_b128 v[156:159], v145 offset:12288
	s_waitcnt lgkmcnt(1)
	v_mfma_f32_16x16x32_bf16 v[46:49], v[130:133], v[160:163], v[46:49]
	v_mfma_f32_16x16x32_bf16 v[42:45], v[134:137], v[160:163], v[42:45]
	v_mfma_f32_16x16x32_bf16 v[38:41], v[148:151], v[160:163], v[38:41]
	v_mfma_f32_16x16x32_bf16 v[34:37], v[152:155], v[160:163], v[34:37]
	ds_read_b128 v[160:163], v145 offset:14336
	s_waitcnt lgkmcnt(1)
	v_mfma_f32_16x16x32_bf16 v[30:33], v[130:133], v[156:159], v[30:33]
	v_mfma_f32_16x16x32_bf16 v[26:29], v[134:137], v[156:159], v[26:29]
	v_mfma_f32_16x16x32_bf16 v[22:25], v[148:151], v[156:159], v[22:25]
	v_mfma_f32_16x16x32_bf16 v[18:21], v[152:155], v[156:159], v[18:21]
	s_waitcnt lgkmcnt(0)
; DI unsigned pack2(float a, float b) { hwf2_t f = {a, b}; return __builtin_bit_cast(unsigned, __builtin_convertvector(f, hwbf2_t)); }
; DI float fsigmoid(float x) { return __builtin_amdgcn_rcpf(1.f + __expf(-x)); }
;     ...
;   const int row0 = m0 + wm * 32 * MI + r16, cbw = n0 + wn * 64;
;   if constexpr (std::is_invocable_v<EP, int, int, int, const f32x4&, const f32x4&, const f32x4&, const f32x4&>) {
; #pragma unroll
;     for (int a = 0; a < MT; ++a) ep(row0 + 16 * a, cbw, q4, acc[a][0], acc[a][1], acc[a][2], acc[a][3]);
;   } else {
; #pragma unroll
;     for (int a = 0; a < MT; ++a)
; #pragma unroll
;       for (int nt = 0; nt < 4; ++nt)
;         ep(row0 + 16 * a, cbw + 16 * nt + 4 * q4, acc[a][nt][0], acc[a][nt][1], acc[a][nt][2], acc[a][nt][3]);
; DI void phase_ffn_up(char* smem, const Params& p, int layer) {
;     ...
;   auto ep = [=](int row, int cb, int q4, const f32x4& c0, const f32x4& c1, const f32x4& c2, const f32x4& c3) {
;     const uint4 o = make_uint4(pack2(c0[0] * fsigmoid(c0[0]) * c0[1], c0[2] * fsigmoid(c0[2]) * c0[3]),
;                                pack2(c1[0] * fsigmoid(c1[0]) * c1[1], c1[2] * fsigmoid(c1[2]) * c1[3]),
;                                pack2(c2[0] * fsigmoid(c2[0]) * c2[1], c2[2] * fsigmoid(c2[2]) * c2[3]),
;                                pack2(c3[0] * fsigmoid(c3[0]) * c3[1], c3[2] * fsigmoid(c3[2]) * c3[3]));
;     *(uint4*)(Hh + (size_t)row * FH + (cb >> 1) + q4 * 8) = o;
;   };
	v_mfma_f32_16x16x32_bf16 v[14:17], v[130:133], v[160:163], v[14:17]
	v_mfma_f32_16x16x32_bf16 v[10:13], v[134:137], v[160:163], v[10:13]
	v_mfma_f32_16x16x32_bf16 v[6:9], v[148:151], v[160:163], v[6:9]
	v_mfma_f32_16x16x32_bf16 v[2:5], v[152:155], v[160:163], v[2:5]
	v_add_u32_e32 v139, v139, v144
	ds_read_b128 v[130:133], v139
	ds_read_b128 v[134:137], v139 offset:2048
	ds_read_b128 v[146:149], v139 offset:4096
	ds_read_b128 v[150:153], v139 offset:6144
	v_add_u32_e32 v138, v138, v144
	ds_read_b128 v[154:157], v138
	ds_read_b128 v[158:161], v138 offset:2048
	s_waitcnt lgkmcnt(1)
	v_mfma_f32_16x16x32_bf16 v[126:129], v[130:133], v[154:157], v[126:129]
	v_mfma_f32_16x16x32_bf16 v[122:125], v[134:137], v[154:157], v[122:125]
	v_mfma_f32_16x16x32_bf16 v[118:121], v[146:149], v[154:157], v[118:121]
	v_mfma_f32_16x16x32_bf16 v[114:117], v[150:153], v[154:157], v[114:117]
	ds_read_b128 v[154:157], v138 offset:4096
	s_waitcnt lgkmcnt(1)
	v_mfma_f32_16x16x32_bf16 v[162:165], v[130:133], v[158:161], v[110:113]
	v_mfma_f32_16x16x32_bf16 v[166:169], v[134:137], v[158:161], v[106:109]
	v_mfma_f32_16x16x32_bf16 v[102:105], v[146:149], v[158:161], v[102:105]
	v_mfma_f32_16x16x32_bf16 v[98:101], v[150:153], v[158:161], v[98:101]
	s_nop 0
	ds_read_b128 v[106:109], v138 offset:6144
	s_waitcnt lgkmcnt(1)
	v_mfma_f32_16x16x32_bf16 v[94:97], v[130:133], v[154:157], v[94:97]
	v_mfma_f32_16x16x32_bf16 v[90:93], v[134:137], v[154:157], v[90:93]
	v_mfma_f32_16x16x32_bf16 v[86:89], v[146:149], v[154:157], v[86:89]
	v_mfma_f32_16x16x32_bf16 v[82:85], v[150:153], v[154:157], v[82:85]
	ds_read_b128 v[110:113], v138 offset:8192
	s_waitcnt lgkmcnt(1)
	v_mfma_f32_16x16x32_bf16 v[78:81], v[130:133], v[106:109], v[78:81]
	v_mfma_f32_16x16x32_bf16 v[74:77], v[134:137], v[106:109], v[74:77]
	v_mfma_f32_16x16x32_bf16 v[70:73], v[146:149], v[106:109], v[70:73]
	v_mfma_f32_16x16x32_bf16 v[66:69], v[150:153], v[106:109], v[66:69]
	ds_read_b128 v[106:109], v138 offset:10240
	s_waitcnt lgkmcnt(1)
	v_mfma_f32_16x16x32_bf16 v[62:65], v[130:133], v[110:113], v[62:65]
	v_mfma_f32_16x16x32_bf16 v[58:61], v[134:137], v[110:113], v[58:61]
	v_mfma_f32_16x16x32_bf16 v[54:57], v[146:149], v[110:113], v[54:57]
	v_mfma_f32_16x16x32_bf16 v[50:53], v[150:153], v[110:113], v[50:53]
	ds_read_b128 v[110:113], v138 offset:12288
	s_waitcnt lgkmcnt(1)
	v_mfma_f32_16x16x32_bf16 v[46:49], v[130:133], v[106:109], v[46:49]
	v_mfma_f32_16x16x32_bf16 v[42:45], v[134:137], v[106:109], v[42:45]
	v_mfma_f32_16x16x32_bf16 v[38:41], v[146:149], v[106:109], v[38:41]
	v_mfma_f32_16x16x32_bf16 v[34:37], v[150:153], v[106:109], v[34:37]
	ds_read_b128 v[106:109], v138 offset:14336
	s_waitcnt lgkmcnt(1)
	v_mfma_f32_16x16x32_bf16 v[30:33], v[130:133], v[110:113], v[30:33]
	v_mfma_f32_16x16x32_bf16 v[26:29], v[134:137], v[110:113], v[26:29]
	v_mfma_f32_16x16x32_bf16 v[22:25], v[146:149], v[110:113], v[22:25]
	v_mfma_f32_16x16x32_bf16 v[18:21], v[150:153], v[110:113], v[18:21]
	s_waitcnt lgkmcnt(0)
	v_mfma_f32_16x16x32_bf16 v[14:17], v[130:133], v[106:109], v[14:17]
	v_mfma_f32_16x16x32_bf16 v[10:13], v[134:137], v[106:109], v[10:13]
	v_mfma_f32_16x16x32_bf16 v[6:9], v[146:149], v[106:109], v[6:9]
	v_mfma_f32_16x16x32_bf16 v[2:5], v[150:153], v[106:109], v[2:5]
	v_or_b32_e32 v107, s38, v142
	v_lshl_add_u32 v110, v141, 7, v107
	v_mul_f32_e32 v107, 0xbfb8aa3b, v126
	v_mul_f32_e32 v108, 0xbfb8aa3b, v128
	v_exp_f32_e32 v107, v107
	v_exp_f32_e32 v109, v108
	v_lshl_or_b32 v106, v143, 6, s39
	v_ashrrev_i32_e32 v108, 1, v106
	v_add_f32_e32 v106, 1.0, v107
	v_add_f32_e32 v107, 1.0, v109
	v_rcp_f32_e32 v106, v106
	v_rcp_f32_e32 v107, v107
	v_mov_b32_e32 v112, v126
	v_mov_b32_e32 v113, v128
	v_mul_f32_e32 v111, 0xbfb8aa3b, v122
	v_pk_mul_f32 v[106:107], v[112:113], v[106:107]
	v_exp_f32_e32 v111, v111
	v_mul_f32_e32 v112, 0xbfb8aa3b, v124
	v_exp_f32_e32 v113, v112
	v_mov_b32_e32 v128, v127
	v_add_f32_e32 v111, 1.0, v111
	v_rcp_f32_e32 v112, v111
	v_add_f32_e32 v111, 1.0, v113
	v_rcp_f32_e32 v113, v111
	v_pk_mul_f32 v[106:107], v[128:129], v[106:107]
	v_mul_f32_e32 v111, 0xbfb8aa3b, v118
	v_cvt_pk_bf16_f32 v126, v106, v107
	v_mov_b32_e32 v106, v122
	v_mov_b32_e32 v107, v124
	v_pk_mul_f32 v[106:107], v[106:107], v[112:113]
	v_exp_f32_e32 v111, v111
	v_mul_f32_e32 v112, 0xbfb8aa3b, v120
	v_exp_f32_e32 v113, v112
	v_mov_b32_e32 v124, v123
	v_add_f32_e32 v111, 1.0, v111
	v_rcp_f32_e32 v112, v111
	v_add_f32_e32 v111, 1.0, v113
	v_rcp_f32_e32 v113, v111
	v_pk_mul_f32 v[106:107], v[124:125], v[106:107]
	v_mul_f32_e32 v111, 0xbfb8aa3b, v114
	v_cvt_pk_bf16_f32 v127, v106, v107
	v_mov_b32_e32 v106, v118
	v_mov_b32_e32 v107, v120
	v_pk_mul_f32 v[106:107], v[106:107], v[112:113]
	v_exp_f32_e32 v111, v111
	v_mul_f32_e32 v112, 0xbfb8aa3b, v116
	v_exp_f32_e32 v113, v112
	v_mov_b32_e32 v120, v119
	v_add_f32_e32 v111, 1.0, v111
	v_rcp_f32_e32 v112, v111
	v_add_f32_e32 v111, 1.0, v113
	v_rcp_f32_e32 v113, v111
	v_pk_mul_f32 v[106:107], v[120:121], v[106:107]
	v_readlane_b32 s52, v253, 40
	v_cvt_pk_bf16_f32 v128, v106, v107
	v_mov_b32_e32 v106, v114
	v_mov_b32_e32 v107, v116
	v_pk_mul_f32 v[106:107], v[106:107], v[112:113]
	v_mov_b32_e32 v116, v115
	v_mul_f32_e32 v111, 0xbfb8aa3b, v162
	v_pk_mul_f32 v[106:107], v[116:117], v[106:107]
	v_readlane_b32 s54, v253, 42
	v_readlane_b32 s55, v253, 43
	v_exp_f32_e32 v111, v111
	v_mul_f32_e32 v114, 0xbfb8aa3b, v164
	v_ashrrev_i32_e32 v109, 31, v108
	v_cvt_pk_bf16_f32 v129, v106, v107
	v_mov_b64_e32 v[106:107], s[54:55]
	s_movk_i32 s38, 0x1600
	v_exp_f32_e32 v114, v114
	v_mad_i64_i32 v[112:113], s[16:17], v110, s38, v[106:107]
	v_lshlrev_b64 v[108:109], 1, v[108:109]
	v_lshl_add_u64 v[112:113], v[112:113], 0, v[108:109]
	v_lshlrev_b32_e32 v190, 4, v140
	v_lshl_add_u64 v[112:113], v[112:113], 0, v[190:191]
	v_add_f32_e32 v111, 1.0, v111
	s_waitcnt vmcnt(0)
	s_barrier
; DI unsigned pack2(float a, float b) { hwf2_t f = {a, b}; return __builtin_bit_cast(unsigned, __builtin_convertvector(f, hwbf2_t)); }
; DI float fsigmoid(float x) { return __builtin_amdgcn_rcpf(1.f + __expf(-x)); }
; DI void phase_ffn_up(char* smem, const Params& p, int layer) {
;     ...
;   auto ep = [=](int row, int cb, int q4, const f32x4& c0, const f32x4& c1, const f32x4& c2, const f32x4& c3) {
;     const uint4 o = make_uint4(pack2(c0[0] * fsigmoid(c0[0]) * c0[1], c0[2] * fsigmoid(c0[2]) * c0[3]),
;                                pack2(c1[0] * fsigmoid(c1[0]) * c1[1], c1[2] * fsigmoid(c1[2]) * c1[3]),
;                                pack2(c2[0] * fsigmoid(c2[0]) * c2[1], c2[2] * fsigmoid(c2[2]) * c2[3]),
;                                pack2(c3[0] * fsigmoid(c3[0]) * c3[1], c3[2] * fsigmoid(c3[2]) * c3[3]));
;     *(uint4*)(Hh + (size_t)row * FH + (cb >> 1) + q4 * 8) = o;
;   };
	global_store_dwordx4 v[112:113], v[126:129], off
	v_rcp_f32_e32 v112, v111
	v_add_f32_e32 v111, 1.0, v114
	v_rcp_f32_e32 v113, v111
	v_mov_b32_e32 v114, v162
	v_mov_b32_e32 v115, v164
	v_mov_b32_e32 v164, v163
	v_pk_mul_f32 v[112:113], v[114:115], v[112:113]
	v_mul_f32_e32 v114, 0xbfb8aa3b, v166
	v_mul_f32_e32 v115, 0xbfb8aa3b, v168
	v_exp_f32_e32 v114, v114
	v_exp_f32_e32 v115, v115
	v_pk_mul_f32 v[112:113], v[164:165], v[112:113]
	v_mov_b32_e32 v116, v166
	v_add_f32_e32 v114, 1.0, v114
	v_add_f32_e32 v115, 1.0, v115
	v_rcp_f32_e32 v114, v114
	v_rcp_f32_e32 v115, v115
	v_cvt_pk_bf16_f32 v112, v112, v113
	v_mov_b32_e32 v117, v168
	v_mul_f32_e32 v113, 0xbfb8aa3b, v102
	v_pk_mul_f32 v[114:115], v[116:117], v[114:115]
	v_exp_f32_e32 v113, v113
	v_mul_f32_e32 v116, 0xbfb8aa3b, v104
	v_exp_f32_e32 v117, v116
	v_mov_b32_e32 v168, v167
	v_add_f32_e32 v113, 1.0, v113
	v_rcp_f32_e32 v116, v113
	v_add_f32_e32 v113, 1.0, v117
	v_rcp_f32_e32 v117, v113
	v_pk_mul_f32 v[114:115], v[168:169], v[114:115]
	v_or_b32_e32 v111, 16, v110
	v_cvt_pk_bf16_f32 v113, v114, v115
	v_mov_b32_e32 v114, v102
	v_mov_b32_e32 v115, v104
	v_mul_f32_e32 v102, 0xbfb8aa3b, v98
	v_pk_mul_f32 v[114:115], v[114:115], v[116:117]
	v_exp_f32_e32 v116, v102
	v_mul_f32_e32 v102, 0xbfb8aa3b, v100
	v_exp_f32_e32 v117, v102
	v_mov_b32_e32 v104, v103
	v_pk_mul_f32 v[102:103], v[104:105], v[114:115]
	v_add_f32_e32 v104, 1.0, v116
	v_add_f32_e32 v105, 1.0, v117
	v_rcp_f32_e32 v104, v104
	v_rcp_f32_e32 v105, v105
	v_cvt_pk_bf16_f32 v114, v102, v103
	v_mov_b32_e32 v102, v98
	v_mov_b32_e32 v103, v100
	v_pk_mul_f32 v[102:103], v[102:103], v[104:105]
	v_mov_b32_e32 v100, v99
	v_pk_mul_f32 v[98:99], v[100:101], v[102:103]
	v_mul_f32_e32 v100, 0xbfb8aa3b, v94
	v_mul_f32_e32 v101, 0xbfb8aa3b, v96
	v_exp_f32_e32 v100, v100
	v_exp_f32_e32 v101, v101
	v_cvt_pk_bf16_f32 v115, v98, v99
	v_mad_i64_i32 v[98:99], s[16:17], v111, s38, v[106:107]
	v_lshl_add_u64 v[98:99], v[98:99], 0, v[108:109]
	v_lshl_add_u64 v[98:99], v[98:99], 0, v[190:191]
	global_store_dwordx4 v[98:99], v[112:115], off
	v_add_f32_e32 v98, 1.0, v100
	v_add_f32_e32 v99, 1.0, v101
	v_rcp_f32_e32 v98, v98
	v_rcp_f32_e32 v99, v99
	v_mov_b32_e32 v100, v94
	v_mov_b32_e32 v101, v96
	v_mul_f32_e32 v94, 0xbfb8aa3b, v90
	v_pk_mul_f32 v[98:99], v[100:101], v[98:99]
	v_exp_f32_e32 v100, v94
	v_mul_f32_e32 v94, 0xbfb8aa3b, v92
	v_exp_f32_e32 v101, v94
	v_mov_b32_e32 v96, v95
	v_pk_mul_f32 v[94:95], v[96:97], v[98:99]
	v_add_f32_e32 v96, 1.0, v100
	v_add_f32_e32 v97, 1.0, v101
	v_rcp_f32_e32 v96, v96
	v_rcp_f32_e32 v97, v97
	v_mov_b32_e32 v98, v90
	v_mul_f32_e32 v90, 0xbfb8aa3b, v86
	v_cvt_pk_bf16_f32 v94, v94, v95
	v_mov_b32_e32 v99, v92
	v_exp_f32_e32 v95, v90
	v_mul_f32_e32 v90, 0xbfb8aa3b, v88
	v_pk_mul_f32 v[96:97], v[98:99], v[96:97]
	v_exp_f32_e32 v98, v90
	v_mov_b32_e32 v92, v91
	v_pk_mul_f32 v[90:91], v[92:93], v[96:97]
	v_add_f32_e32 v92, 1.0, v95
	v_add_f32_e32 v93, 1.0, v98
	v_rcp_f32_e32 v92, v92
	v_rcp_f32_e32 v93, v93
	v_cvt_pk_bf16_f32 v95, v90, v91
	v_mov_b32_e32 v90, v86
	v_mov_b32_e32 v91, v88
	v_mul_f32_e32 v86, 0xbfb8aa3b, v82
	v_pk_mul_f32 v[90:91], v[90:91], v[92:93]
	v_exp_f32_e32 v92, v86
	v_mul_f32_e32 v86, 0xbfb8aa3b, v84
	v_exp_f32_e32 v93, v86
	v_mov_b32_e32 v88, v87
	v_pk_mul_f32 v[86:87], v[88:89], v[90:91]
	v_add_f32_e32 v88, 1.0, v92
	v_add_f32_e32 v89, 1.0, v93
	v_rcp_f32_e32 v88, v88
	v_rcp_f32_e32 v89, v89
	v_cvt_pk_bf16_f32 v96, v86, v87
	v_mov_b32_e32 v86, v82
	v_mov_b32_e32 v87, v84
	v_pk_mul_f32 v[86:87], v[86:87], v[88:89]
	v_mov_b32_e32 v84, v83
	v_pk_mul_f32 v[82:83], v[84:85], v[86:87]
	v_mul_f32_e32 v84, 0xbfb8aa3b, v78
	v_mul_f32_e32 v85, 0xbfb8aa3b, v80
	v_or_b32_e32 v102, 32, v110
	v_exp_f32_e32 v84, v84
	v_exp_f32_e32 v85, v85
	v_cvt_pk_bf16_f32 v97, v82, v83
	v_mad_i64_i32 v[82:83], s[16:17], v102, s38, v[106:107]
	v_lshl_add_u64 v[82:83], v[82:83], 0, v[108:109]
	v_lshl_add_u64 v[82:83], v[82:83], 0, v[190:191]
	global_store_dwordx4 v[82:83], v[94:97], off
	v_add_f32_e32 v82, 1.0, v84
	v_add_f32_e32 v83, 1.0, v85
	v_rcp_f32_e32 v82, v82
	v_rcp_f32_e32 v83, v83
	v_mov_b32_e32 v84, v78
	v_mov_b32_e32 v85, v80
	v_mul_f32_e32 v78, 0xbfb8aa3b, v74
	v_pk_mul_f32 v[82:83], v[84:85], v[82:83]
	v_exp_f32_e32 v84, v78
	v_mul_f32_e32 v78, 0xbfb8aa3b, v76
	v_exp_f32_e32 v85, v78
	v_mov_b32_e32 v80, v79
	v_pk_mul_f32 v[78:79], v[80:81], v[82:83]
	v_add_f32_e32 v80, 1.0, v84
	v_add_f32_e32 v81, 1.0, v85
	v_rcp_f32_e32 v80, v80
	v_rcp_f32_e32 v81, v81
	v_mov_b32_e32 v82, v74
	v_mul_f32_e32 v74, 0xbfb8aa3b, v70
	v_cvt_pk_bf16_f32 v78, v78, v79
	v_mov_b32_e32 v83, v76
	v_exp_f32_e32 v79, v74
	v_mul_f32_e32 v74, 0xbfb8aa3b, v72
	v_pk_mul_f32 v[80:81], v[82:83], v[80:81]
	v_exp_f32_e32 v82, v74
	v_mov_b32_e32 v76, v75
	v_pk_mul_f32 v[74:75], v[76:77], v[80:81]
	v_add_f32_e32 v76, 1.0, v79
	v_add_f32_e32 v77, 1.0, v82
	v_rcp_f32_e32 v76, v76
	v_rcp_f32_e32 v77, v77
	v_cvt_pk_bf16_f32 v79, v74, v75
	v_mov_b32_e32 v74, v70
	v_mov_b32_e32 v75, v72
	v_mul_f32_e32 v70, 0xbfb8aa3b, v66
	v_pk_mul_f32 v[74:75], v[74:75], v[76:77]
	v_exp_f32_e32 v76, v70
	v_mul_f32_e32 v70, 0xbfb8aa3b, v68
	v_exp_f32_e32 v77, v70
	v_mov_b32_e32 v72, v71
	v_pk_mul_f32 v[70:71], v[72:73], v[74:75]
	v_add_f32_e32 v72, 1.0, v76
	v_add_f32_e32 v73, 1.0, v77
	v_rcp_f32_e32 v72, v72
	v_rcp_f32_e32 v73, v73
	v_cvt_pk_bf16_f32 v80, v70, v71
	v_mov_b32_e32 v70, v66
	v_mov_b32_e32 v71, v68
	v_pk_mul_f32 v[70:71], v[70:71], v[72:73]
	v_mov_b32_e32 v68, v67
	v_pk_mul_f32 v[66:67], v[68:69], v[70:71]
	v_mul_f32_e32 v68, 0xbfb8aa3b, v62
	v_mul_f32_e32 v69, 0xbfb8aa3b, v64
	v_or_b32_e32 v86, 48, v110
	v_exp_f32_e32 v68, v68
	v_exp_f32_e32 v69, v69
; DI unsigned pack2(float a, float b) { hwf2_t f = {a, b}; return __builtin_bit_cast(unsigned, __builtin_convertvector(f, hwbf2_t)); }
; DI float fsigmoid(float x) { return __builtin_amdgcn_rcpf(1.f + __expf(-x)); }
; DI void phase_ffn_up(char* smem, const Params& p, int layer) {
;     ...
;   auto ep = [=](int row, int cb, int q4, const f32x4& c0, const f32x4& c1, const f32x4& c2, const f32x4& c3) {
;     const uint4 o = make_uint4(pack2(c0[0] * fsigmoid(c0[0]) * c0[1], c0[2] * fsigmoid(c0[2]) * c0[3]),
;                                pack2(c1[0] * fsigmoid(c1[0]) * c1[1], c1[2] * fsigmoid(c1[2]) * c1[3]),
;                                pack2(c2[0] * fsigmoid(c2[0]) * c2[1], c2[2] * fsigmoid(c2[2]) * c2[3]),
;                                pack2(c3[0] * fsigmoid(c3[0]) * c3[1], c3[2] * fsigmoid(c3[2]) * c3[3]));
;     *(uint4*)(Hh + (size_t)row * FH + (cb >> 1) + q4 * 8) = o;
;   };
	v_cvt_pk_bf16_f32 v81, v66, v67
	v_mad_i64_i32 v[66:67], s[16:17], v86, s38, v[106:107]
	v_lshl_add_u64 v[66:67], v[66:67], 0, v[108:109]
	v_lshl_add_u64 v[66:67], v[66:67], 0, v[190:191]
	global_store_dwordx4 v[66:67], v[78:81], off
	v_add_f32_e32 v66, 1.0, v68
	v_add_f32_e32 v67, 1.0, v69
	v_rcp_f32_e32 v66, v66
	v_rcp_f32_e32 v67, v67
	v_mov_b32_e32 v68, v62
	v_mov_b32_e32 v69, v64
	v_mul_f32_e32 v62, 0xbfb8aa3b, v58
	v_pk_mul_f32 v[66:67], v[68:69], v[66:67]
	v_exp_f32_e32 v68, v62
	v_mul_f32_e32 v62, 0xbfb8aa3b, v60
	v_exp_f32_e32 v69, v62
	v_mov_b32_e32 v64, v63
	v_pk_mul_f32 v[62:63], v[64:65], v[66:67]
	v_add_f32_e32 v64, 1.0, v68
	v_add_f32_e32 v65, 1.0, v69
	v_rcp_f32_e32 v64, v64
	v_rcp_f32_e32 v65, v65
	v_mov_b32_e32 v66, v58
	v_mul_f32_e32 v58, 0xbfb8aa3b, v54
	v_cvt_pk_bf16_f32 v62, v62, v63
	v_mov_b32_e32 v67, v60
	v_exp_f32_e32 v63, v58
	v_mul_f32_e32 v58, 0xbfb8aa3b, v56
	v_pk_mul_f32 v[64:65], v[66:67], v[64:65]
	v_exp_f32_e32 v66, v58
	v_mov_b32_e32 v60, v59
	v_pk_mul_f32 v[58:59], v[60:61], v[64:65]
	v_add_f32_e32 v60, 1.0, v63
	v_add_f32_e32 v61, 1.0, v66
	v_rcp_f32_e32 v60, v60
	v_rcp_f32_e32 v61, v61
	v_cvt_pk_bf16_f32 v63, v58, v59
	v_mov_b32_e32 v58, v54
	v_mov_b32_e32 v59, v56
	v_mul_f32_e32 v54, 0xbfb8aa3b, v50
	v_pk_mul_f32 v[58:59], v[58:59], v[60:61]
	v_exp_f32_e32 v60, v54
	v_mul_f32_e32 v54, 0xbfb8aa3b, v52
	v_exp_f32_e32 v61, v54
	v_mov_b32_e32 v56, v55
	v_pk_mul_f32 v[54:55], v[56:57], v[58:59]
	v_add_f32_e32 v56, 1.0, v60
	v_add_f32_e32 v57, 1.0, v61
	v_rcp_f32_e32 v56, v56
	v_rcp_f32_e32 v57, v57
	v_cvt_pk_bf16_f32 v64, v54, v55
	v_mov_b32_e32 v54, v50
	v_mov_b32_e32 v55, v52
	v_pk_mul_f32 v[54:55], v[54:55], v[56:57]
	v_mov_b32_e32 v52, v51
	v_pk_mul_f32 v[50:51], v[52:53], v[54:55]
	v_mul_f32_e32 v52, 0xbfb8aa3b, v46
	v_mul_f32_e32 v53, 0xbfb8aa3b, v48
	v_or_b32_e32 v70, 64, v110
	v_exp_f32_e32 v52, v52
	v_exp_f32_e32 v53, v53
	v_cvt_pk_bf16_f32 v65, v50, v51
	v_mad_i64_i32 v[50:51], s[16:17], v70, s38, v[106:107]
	v_lshl_add_u64 v[50:51], v[50:51], 0, v[108:109]
	v_lshl_add_u64 v[50:51], v[50:51], 0, v[190:191]
	global_store_dwordx4 v[50:51], v[62:65], off
	v_add_f32_e32 v50, 1.0, v52
	v_add_f32_e32 v51, 1.0, v53
	v_rcp_f32_e32 v50, v50
	v_rcp_f32_e32 v51, v51
	v_mov_b32_e32 v52, v46
	v_mov_b32_e32 v53, v48
	v_mul_f32_e32 v46, 0xbfb8aa3b, v42
	v_pk_mul_f32 v[50:51], v[52:53], v[50:51]
	v_exp_f32_e32 v52, v46
	v_mul_f32_e32 v46, 0xbfb8aa3b, v44
	v_exp_f32_e32 v53, v46
	v_mov_b32_e32 v48, v47
	v_pk_mul_f32 v[46:47], v[48:49], v[50:51]
	v_add_f32_e32 v48, 1.0, v52
	v_add_f32_e32 v49, 1.0, v53
	v_rcp_f32_e32 v48, v48
	v_rcp_f32_e32 v49, v49
	v_mov_b32_e32 v50, v42
	v_mul_f32_e32 v42, 0xbfb8aa3b, v38
	v_cvt_pk_bf16_f32 v46, v46, v47
	v_mov_b32_e32 v51, v44
	v_exp_f32_e32 v47, v42
	v_mul_f32_e32 v42, 0xbfb8aa3b, v40
	v_pk_mul_f32 v[48:49], v[50:51], v[48:49]
	v_exp_f32_e32 v50, v42
	v_mov_b32_e32 v44, v43
	v_pk_mul_f32 v[42:43], v[44:45], v[48:49]
	v_add_f32_e32 v44, 1.0, v47
	v_add_f32_e32 v45, 1.0, v50
	v_rcp_f32_e32 v44, v44
	v_rcp_f32_e32 v45, v45
	v_cvt_pk_bf16_f32 v47, v42, v43
	v_mov_b32_e32 v42, v38
	v_mov_b32_e32 v43, v40
	v_mul_f32_e32 v38, 0xbfb8aa3b, v34
	v_pk_mul_f32 v[42:43], v[42:43], v[44:45]
	v_exp_f32_e32 v44, v38
	v_mul_f32_e32 v38, 0xbfb8aa3b, v36
	v_exp_f32_e32 v45, v38
	v_mov_b32_e32 v40, v39
	v_pk_mul_f32 v[38:39], v[40:41], v[42:43]
	v_add_f32_e32 v40, 1.0, v44
	v_add_f32_e32 v41, 1.0, v45
	v_rcp_f32_e32 v40, v40
	v_rcp_f32_e32 v41, v41
	v_cvt_pk_bf16_f32 v48, v38, v39
	v_mov_b32_e32 v38, v34
	v_mov_b32_e32 v39, v36
	v_pk_mul_f32 v[38:39], v[38:39], v[40:41]
	v_mov_b32_e32 v36, v35
	v_pk_mul_f32 v[34:35], v[36:37], v[38:39]
	v_mul_f32_e32 v36, 0xbfb8aa3b, v30
	v_mul_f32_e32 v37, 0xbfb8aa3b, v32
	v_or_b32_e32 v54, 0x50, v110
	v_exp_f32_e32 v36, v36
	v_exp_f32_e32 v37, v37
	v_cvt_pk_bf16_f32 v49, v34, v35
	v_mad_i64_i32 v[34:35], s[16:17], v54, s38, v[106:107]
	v_lshl_add_u64 v[34:35], v[34:35], 0, v[108:109]
	v_lshl_add_u64 v[34:35], v[34:35], 0, v[190:191]
	global_store_dwordx4 v[34:35], v[46:49], off
	v_add_f32_e32 v34, 1.0, v36
; DI unsigned pack2(float a, float b) { hwf2_t f = {a, b}; return __builtin_bit_cast(unsigned, __builtin_convertvector(f, hwbf2_t)); }
; DI float fsigmoid(float x) { return __builtin_amdgcn_rcpf(1.f + __expf(-x)); }
; template <int TMI, class F>
; DI void for_tiles_xcd(int MT, int NT, const F& f) {
;     ...
;     for (int c = x; c * 32 < total_full; c += 8)
;       for (int kk = slot; kk < 32; kk += nslots) {
;         const int L = c * 32 + kk;
;         if (L >= total_full) break;
;         int mt, nt; decode(L, mt, nt);
;         f(mt * 256, nt, std::integral_constant<int, 4>{});
; DI void phase_ffn_up(char* smem, const Params& p, int layer) {
;     ...
;   auto ep = [=](int row, int cb, int q4, const f32x4& c0, const f32x4& c1, const f32x4& c2, const f32x4& c3) {
;     const uint4 o = make_uint4(pack2(c0[0] * fsigmoid(c0[0]) * c0[1], c0[2] * fsigmoid(c0[2]) * c0[3]),
;                                pack2(c1[0] * fsigmoid(c1[0]) * c1[1], c1[2] * fsigmoid(c1[2]) * c1[3]),
;                                pack2(c2[0] * fsigmoid(c2[0]) * c2[1], c2[2] * fsigmoid(c2[2]) * c2[3]),
;                                pack2(c3[0] * fsigmoid(c3[0]) * c3[1], c3[2] * fsigmoid(c3[2]) * c3[3]));
;     *(uint4*)(Hh + (size_t)row * FH + (cb >> 1) + q4 * 8) = o;
;   };
	v_add_f32_e32 v35, 1.0, v37
	v_rcp_f32_e32 v34, v34
	v_rcp_f32_e32 v35, v35
	v_mov_b32_e32 v36, v30
	v_mov_b32_e32 v37, v32
	v_mul_f32_e32 v30, 0xbfb8aa3b, v26
	v_pk_mul_f32 v[34:35], v[36:37], v[34:35]
	v_exp_f32_e32 v36, v30
	v_mul_f32_e32 v30, 0xbfb8aa3b, v28
	v_exp_f32_e32 v37, v30
	v_mov_b32_e32 v32, v31
	v_pk_mul_f32 v[30:31], v[32:33], v[34:35]
	v_add_f32_e32 v32, 1.0, v36
	v_add_f32_e32 v33, 1.0, v37
	v_rcp_f32_e32 v32, v32
	v_rcp_f32_e32 v33, v33
	v_mov_b32_e32 v34, v26
	v_mul_f32_e32 v26, 0xbfb8aa3b, v22
	v_cvt_pk_bf16_f32 v30, v30, v31
	v_mov_b32_e32 v35, v28
	v_exp_f32_e32 v31, v26
	v_mul_f32_e32 v26, 0xbfb8aa3b, v24
	v_pk_mul_f32 v[32:33], v[34:35], v[32:33]
	v_exp_f32_e32 v34, v26
	v_mov_b32_e32 v28, v27
	v_pk_mul_f32 v[26:27], v[28:29], v[32:33]
	v_add_f32_e32 v28, 1.0, v31
	v_add_f32_e32 v29, 1.0, v34
	v_rcp_f32_e32 v28, v28
	v_rcp_f32_e32 v29, v29
	v_cvt_pk_bf16_f32 v31, v26, v27
	v_mov_b32_e32 v26, v22
	v_mov_b32_e32 v27, v24
	v_mul_f32_e32 v22, 0xbfb8aa3b, v18
	v_pk_mul_f32 v[26:27], v[26:27], v[28:29]
	v_exp_f32_e32 v28, v22
	v_mul_f32_e32 v22, 0xbfb8aa3b, v20
	v_exp_f32_e32 v29, v22
	v_mov_b32_e32 v24, v23
	v_pk_mul_f32 v[22:23], v[24:25], v[26:27]
	v_add_f32_e32 v24, 1.0, v28
	v_add_f32_e32 v25, 1.0, v29
	v_rcp_f32_e32 v24, v24
	v_rcp_f32_e32 v25, v25
	v_cvt_pk_bf16_f32 v32, v22, v23
	v_mov_b32_e32 v22, v18
	v_mov_b32_e32 v23, v20
	v_pk_mul_f32 v[22:23], v[22:23], v[24:25]
	v_mov_b32_e32 v20, v19
	v_pk_mul_f32 v[18:19], v[20:21], v[22:23]
	v_mul_f32_e32 v20, 0xbfb8aa3b, v14
	v_mul_f32_e32 v21, 0xbfb8aa3b, v16
	v_or_b32_e32 v38, 0x60, v110
	v_exp_f32_e32 v20, v20
	v_exp_f32_e32 v21, v21
	v_cvt_pk_bf16_f32 v33, v18, v19
	v_mad_i64_i32 v[18:19], s[16:17], v38, s38, v[106:107]
	v_lshl_add_u64 v[18:19], v[18:19], 0, v[108:109]
	v_lshl_add_u64 v[18:19], v[18:19], 0, v[190:191]
	global_store_dwordx4 v[18:19], v[30:33], off
	v_add_f32_e32 v18, 1.0, v20
	v_add_f32_e32 v19, 1.0, v21
	v_rcp_f32_e32 v18, v18
	v_rcp_f32_e32 v19, v19
	v_mov_b32_e32 v20, v14
	v_mov_b32_e32 v21, v16
	v_mul_f32_e32 v14, 0xbfb8aa3b, v10
	v_pk_mul_f32 v[18:19], v[20:21], v[18:19]
	v_exp_f32_e32 v20, v14
	v_mul_f32_e32 v14, 0xbfb8aa3b, v12
	v_exp_f32_e32 v21, v14
	v_mov_b32_e32 v16, v15
	v_pk_mul_f32 v[14:15], v[16:17], v[18:19]
	v_add_f32_e32 v16, 1.0, v20
	v_add_f32_e32 v17, 1.0, v21
	v_rcp_f32_e32 v16, v16
	v_rcp_f32_e32 v17, v17
	v_mov_b32_e32 v18, v10
	v_mul_f32_e32 v10, 0xbfb8aa3b, v6
	v_cvt_pk_bf16_f32 v14, v14, v15
	v_mov_b32_e32 v19, v12
	v_exp_f32_e32 v15, v10
	v_mul_f32_e32 v10, 0xbfb8aa3b, v8
	v_pk_mul_f32 v[16:17], v[18:19], v[16:17]
	v_exp_f32_e32 v18, v10
	v_mov_b32_e32 v12, v11
	v_pk_mul_f32 v[10:11], v[12:13], v[16:17]
	v_add_f32_e32 v12, 1.0, v15
	v_add_f32_e32 v13, 1.0, v18
	v_rcp_f32_e32 v12, v12
	v_rcp_f32_e32 v13, v13
	v_cvt_pk_bf16_f32 v15, v10, v11
	v_mov_b32_e32 v10, v6
	v_mov_b32_e32 v11, v8
	v_mul_f32_e32 v6, 0xbfb8aa3b, v2
	v_pk_mul_f32 v[10:11], v[10:11], v[12:13]
	v_exp_f32_e32 v12, v6
	v_mul_f32_e32 v6, 0xbfb8aa3b, v4
	v_exp_f32_e32 v13, v6
	v_mov_b32_e32 v8, v7
	v_pk_mul_f32 v[6:7], v[8:9], v[10:11]
	v_add_f32_e32 v8, 1.0, v12
	v_add_f32_e32 v9, 1.0, v13
	v_rcp_f32_e32 v8, v8
	v_rcp_f32_e32 v9, v9
	v_cvt_pk_bf16_f32 v16, v6, v7
	v_mov_b32_e32 v6, v2
	v_mov_b32_e32 v7, v4
	v_pk_mul_f32 v[6:7], v[6:7], v[8:9]
	v_mov_b32_e32 v4, v3
	v_or_b32_e32 v22, 0x70, v110
	v_pk_mul_f32 v[2:3], v[4:5], v[6:7]
	s_add_i32 s37, s37, s30
	v_cvt_pk_bf16_f32 v17, v2, v3
	v_mad_i64_i32 v[2:3], s[16:17], v22, s38, v[106:107]
	v_lshl_add_u64 v[2:3], v[2:3], 0, v[108:109]
	s_cmp_gt_i32 s37, 31
	v_lshl_add_u64 v[2:3], v[2:3], 0, v[190:191]
	s_cselect_b64 s[16:17], -1, 0
	v_readlane_b32 s53, v253, 41
	v_readlane_b32 s56, v253, 44
	v_readlane_b32 s57, v253, 45
	v_readlane_b32 s58, v253, 46
	v_readlane_b32 s59, v253, 47
	v_readlane_b32 s60, v253, 48
	v_readlane_b32 s61, v253, 49
	v_readlane_b32 s62, v253, 50
	v_readlane_b32 s63, v253, 51
	v_readlane_b32 s64, v253, 52
	v_readlane_b32 s65, v253, 53
	v_readlane_b32 s66, v253, 54
	v_readlane_b32 s67, v253, 55
	global_store_dwordx4 v[2:3], v[14:17], off
	s_branch .LBB0_68

; DI int tid_() { int t = threadIdx.x; asm volatile("" : "+v"(t)); return t; }
;     ...
;   const int tid = tid_(), w = tid >> 6, l = tid & 63, r16 = l & 15, q4 = l >> 4;
;   const int wm = w >> 2, wn = w & 3;
;   f32x4 acc[MT][4];
; #pragma unroll
;   for (int a = 0; a < MT; ++a)
; #pragma unroll
;     for (int b = 0; b < 4; ++b) { acc[a][b][0] = 0.f; acc[a][b][1] = 0.f; acc[a][b][2] = 0.f; acc[a][b][3] = 0.f; }
;   const int srow = tid >> 3, slog = (tid & 7) ^ ((tid >> 4) & 7);
;   const bf16_t* Ag = A + (size_t)(m0 + srow) * lda + slog * 8;
;   const bf16_t* Bg0 = B + (size_t)min(n0 + srow, N - 1) * ldb + slog * 8;
;   const bf16_t* Bg1 = B + (size_t)min(n0 + srow + 64, N - 1) * ldb + slog * 8;
;   const bf16_t* Bg2 = B + (size_t)min(n0 + srow + 128, N - 1) * ldb + slog * 8;
;   const bf16_t* Bg3 = B + (size_t)min(n0 + srow + 192, N - 1) * ldb + slog * 8;
;   char* wbase = smem + w * 1024;
;     ...
;   const int nk = K >> 6;
;   __syncthreads();
;   STAGE_TILE(0, 0)
;   asm volatile("s_waitcnt vmcnt(0)" ::: "memory");
;   __syncthreads();
.LBB0_564:
	v_mov_b32_e32 v16, v0
	s_lshl_b32 s4, s5, 8
	v_readlane_b32 s52, v253, 40
	v_ashrrev_i32_e32 v4, 3, v16
	v_lshrrev_b32_e32 v17, 4, v16
	v_add_u32_e32 v2, s4, v4
	v_xor_b32_e32 v5, v17, v16
	v_ashrrev_i32_e32 v3, 31, v2
	v_ashrrev_i32_e32 v14, 6, v16
	v_lshlrev_b64 v[2:3], 11, v[2:3]
	v_readlane_b32 s53, v253, 41
	v_lshlrev_b32_e32 v5, 4, v5
	s_lshl_b32 s22, s10, 8
	v_lshl_add_u64 v[2:3], s[52:53], 0, v[2:3]
	v_and_b32_e32 v190, 0x70, v5
	v_lshl_add_u32 v144, v14, 10, 0
	v_lshl_add_u64 v[130:131], v[2:3], 0, v[190:191]
	v_add_u32_e32 v2, s22, v4
	v_readfirstlane_b32 s2, v144
	v_add_u32_e32 v3, 0x2000, v144
	v_min_i32_e32 v4, 0x9bf, v2
	v_min_i32_e32 v8, 0x97f, v2
	s_mov_b64 s[6:7], 0x20000
	s_mov_b32 m0, s2
	v_readfirstlane_b32 s2, v3
	v_add_u32_e32 v3, 0x4000, v144
	v_and_b32_e32 v142, 3, v14
	v_ashrrev_i32_e32 v5, 31, v4
	v_ashrrev_i32_e32 v9, 31, v8
	v_min_i32_e32 v10, 0x93f, v2
	s_mov_b64 s[8:9], 0x40000
	s_waitcnt vmcnt(63) expcnt(7) lgkmcnt(15)
	s_barrier
	global_load_lds_dwordx4 v[130:131], off
	v_lshl_add_u64 v[14:15], v[130:131], 0, s[6:7]
	s_mov_b32 m0, s2
	v_readfirstlane_b32 s2, v3
	v_add_u32_e32 v3, 0x6000, v144
	v_lshlrev_b64 v[4:5], 11, v[4:5]
	v_lshlrev_b64 v[8:9], 11, v[8:9]
	v_ashrrev_i32_e32 v11, 31, v10
	v_min_i32_e32 v12, 0x8ff, v2
	s_mov_b64 s[12:13], 0x60000
	global_load_lds_dwordx4 v[14:15], off
	v_lshl_add_u64 v[14:15], v[130:131], 0, s[8:9]
	s_mov_b32 m0, s2
	v_readfirstlane_b32 s2, v3
	v_add_u32_e32 v3, 0x8000, v144
	v_lshl_add_u64 v[6:7], s[20:21], 0, v[4:5]
	v_lshl_add_u64 v[8:9], s[20:21], 0, v[8:9]
	v_lshlrev_b64 v[10:11], 11, v[10:11]
	v_ashrrev_i32_e32 v13, 31, v12
	global_load_lds_dwordx4 v[14:15], off
	v_lshl_add_u64 v[14:15], v[130:131], 0, s[12:13]
	s_mov_b32 m0, s2
	v_readfirstlane_b32 s2, v3
	v_add_u32_e32 v3, 0xa000, v144
	v_lshl_add_u64 v[6:7], v[6:7], 0, v[190:191]
	v_lshl_add_u64 v[8:9], v[8:9], 0, v[190:191]
	v_lshl_add_u64 v[10:11], s[20:21], 0, v[10:11]
	v_lshlrev_b64 v[12:13], 11, v[12:13]
	global_load_lds_dwordx4 v[14:15], off
	s_mov_b32 m0, s2
	v_readfirstlane_b32 s2, v3
	v_add_u32_e32 v3, 0xc000, v144
	v_lshl_add_u64 v[8:9], v[8:9], 0, s[6:7]
	v_lshl_add_u64 v[10:11], v[10:11], 0, v[190:191]
	v_lshl_add_u64 v[12:13], s[20:21], 0, v[12:13]
	global_load_lds_dwordx4 v[6:7], off
	s_mov_b32 m0, s2
	v_readfirstlane_b32 s2, v3
	v_add_u32_e32 v3, 0xe000, v144
	v_lshl_add_u64 v[10:11], v[10:11], 0, s[8:9]
	v_lshl_add_u64 v[12:13], v[12:13], 0, v[190:191]
	global_load_lds_dwordx4 v[8:9], off
	s_mov_b32 m0, s2
	v_readfirstlane_b32 s2, v3
	v_lshl_add_u64 v[12:13], v[12:13], 0, s[12:13]
	global_load_lds_dwordx4 v[10:11], off
	s_mov_b32 m0, s2
	v_and_b32_e32 v162, 15, v16
	global_load_lds_dwordx4 v[12:13], off
	v_ashrrev_i32_e32 v141, 8, v16
	v_bfe_u32 v140, v16, 4, 2
	v_bfe_u32 v3, v16, 1, 3
	v_lshlrev_b32_e32 v6, 7, v162
	v_lshl_or_b32 v147, v141, 14, v6
	v_lshl_or_b32 v146, v142, 13, v6
	v_bitop3_b32 v6, v17, v3, 3 bitop3:0x6c
	v_bitop3_b32 v3, v140, v3, 4 bitop3:0x36
	v_lshlrev_b32_e32 v143, 4, v3
	v_ashrrev_i32_e32 v3, 31, v2
	s_mov_b64 s[2:3], 0x8ff
	v_cmp_gt_i64_e32 vcc, s[2:3], v[2:3]
	v_lshlrev_b32_e32 v145, 4, v6
	v_bitop3_b32 v8, v17, 7, v16 bitop3:0x48
	v_cndmask_b32_e32 v7, 0, v3, vcc
	v_cndmask_b32_e32 v6, v235, v2, vcc
	v_lshlrev_b64 v[6:7], 11, v[6:7]
	v_lshlrev_b32_e32 v8, 4, v8
	s_mov_b64 s[2:3], 0x93f
	v_or_b32_e32 v6, v6, v8
	v_cmp_gt_i64_e32 vcc, s[2:3], v[2:3]
	s_mov_b64 s[2:3], 0x97f
	v_lshl_add_u64 v[132:133], s[92:93], 0, v[6:7]
	v_cndmask_b32_e32 v7, 0, v3, vcc
	v_cndmask_b32_e32 v6, v236, v2, vcc
	v_cmp_gt_i64_e32 vcc, s[2:3], v[2:3]
	s_waitcnt vmcnt(0)
	v_lshlrev_b64 v[6:7], 11, v[6:7]
	v_or_b32_e32 v6, v6, v8
	v_cndmask_b32_e32 v3, 0, v3, vcc
	v_cndmask_b32_e32 v2, v237, v2, vcc
	v_lshlrev_b64 v[2:3], 11, v[2:3]
	v_or_b32_e32 v2, v2, v8
	v_lshl_add_u64 v[136:137], s[34:35], 0, v[2:3]
	v_or_b32_e32 v4, v4, v8
	v_mov_b32_e32 v2, 0
	s_mov_b32 s5, 0
	v_lshl_add_u64 v[134:135], s[90:91], 0, v[6:7]
	v_lshl_add_u64 v[138:139], s[26:27], 0, v[4:5]
	s_mov_b64 s[2:3], 0
	v_mov_b32_e32 v3, v2
	v_mov_b32_e32 v4, v2
	v_mov_b32_e32 v5, v2
	v_mov_b32_e32 v6, v2
	v_mov_b32_e32 v7, v2
	v_mov_b32_e32 v8, v2
	v_mov_b32_e32 v9, v2
	v_mov_b32_e32 v10, v2
	v_mov_b32_e32 v11, v2
	v_mov_b32_e32 v12, v2
	v_mov_b32_e32 v13, v2
	v_mov_b32_e32 v14, v2
	v_mov_b32_e32 v15, v2
	v_mov_b32_e32 v16, v2
	v_mov_b32_e32 v17, v2
	v_mov_b32_e32 v18, v2
	v_mov_b32_e32 v19, v2
	v_mov_b32_e32 v20, v2
	v_mov_b32_e32 v21, v2
	v_mov_b32_e32 v22, v2
	v_mov_b32_e32 v23, v2
	v_mov_b32_e32 v24, v2
	v_mov_b32_e32 v25, v2
	v_mov_b32_e32 v26, v2
	v_mov_b32_e32 v27, v2
	v_mov_b32_e32 v28, v2
	v_mov_b32_e32 v29, v2
	v_mov_b32_e32 v30, v2
	v_mov_b32_e32 v31, v2
	v_mov_b32_e32 v32, v2
	v_mov_b32_e32 v33, v2
	v_mov_b32_e32 v34, v2
	v_mov_b32_e32 v35, v2
	v_mov_b32_e32 v36, v2
	v_mov_b32_e32 v37, v2
	v_mov_b32_e32 v38, v2
	v_mov_b32_e32 v39, v2
	v_mov_b32_e32 v40, v2
	v_mov_b32_e32 v41, v2
	v_mov_b32_e32 v42, v2
	v_mov_b32_e32 v43, v2
	v_mov_b32_e32 v44, v2
	v_mov_b32_e32 v45, v2
	v_mov_b32_e32 v46, v2
	v_mov_b32_e32 v47, v2
	v_mov_b32_e32 v48, v2
	v_mov_b32_e32 v49, v2
	v_mov_b32_e32 v50, v2
	v_mov_b32_e32 v51, v2
	v_mov_b32_e32 v52, v2
	v_mov_b32_e32 v53, v2
	v_mov_b32_e32 v54, v2
	v_mov_b32_e32 v55, v2
	v_mov_b32_e32 v56, v2
	v_mov_b32_e32 v57, v2
	v_mov_b32_e32 v58, v2
	v_mov_b32_e32 v59, v2
	v_mov_b32_e32 v60, v2
	v_mov_b32_e32 v61, v2
	v_mov_b32_e32 v62, v2
	v_mov_b32_e32 v63, v2
	v_mov_b32_e32 v64, v2
	v_mov_b32_e32 v65, v2
	v_mov_b32_e32 v66, v2
	v_mov_b32_e32 v67, v2
	v_mov_b32_e32 v68, v2
	v_mov_b32_e32 v69, v2
	v_mov_b32_e32 v70, v2
	v_mov_b32_e32 v71, v2
	v_mov_b32_e32 v72, v2
	v_mov_b32_e32 v73, v2
	v_mov_b32_e32 v74, v2
	v_mov_b32_e32 v75, v2
	v_mov_b32_e32 v76, v2
	v_mov_b32_e32 v77, v2
	v_mov_b32_e32 v78, v2
	v_mov_b32_e32 v79, v2
	v_mov_b32_e32 v80, v2
	v_mov_b32_e32 v81, v2
	s_waitcnt vmcnt(0)
; #define MFMA16(a, b, c) __builtin_amdgcn_mfma_f32_16x16x32_bf16((a), (b), (c), 0, 0, 0)
;     ...
;   for (int kt = 0; kt < nk; ++kt) {
;     const int buf = kt & 1;
;     const char* cA = smem + buf * STAGE + (wm * 32 * MI + r16) * 128;
;     const char* cB = smem + buf * STAGE + 32768 + (wn * 64 + r16) * 128;
; #pragma unroll
;     for (int k2 = 0; k2 < 2; ++k2) {
;       if (k2 == 1 && kt + 1 < nk) STAGE_TILE(buf ^ 1, (kt + 1) * 64)
;       const int po = ((4 * k2 + q4) ^ swz) * 16;
;       bf16x8 bf[4];
; #pragma unroll
;       for (int nt = 0; nt < 4; ++nt) bf[nt] = *(const bf16x8*)(cB + nt * 16 * 128 + po);
;       bf16x8 afc = *(const bf16x8*)(cA + po);
; #pragma unroll
;       for (int a = 0; a < MT; ++a) {
;         bf16x8 afn = afc;
;         if (a + 1 < MT) afn = *(const bf16x8*)(cA + (a + 1) * 16 * 128 + po);
;         __builtin_amdgcn_sched_barrier(0);
; #pragma unroll
;         for (int nt = 0; nt < 4; ++nt) acc[a][nt] = MFMA16(bf[nt], afc, acc[a][nt]);
;         __builtin_amdgcn_sched_barrier(0);
;         afc = afn;
;       }
	v_mov_b32_e32 v82, v2
	v_mov_b32_e32 v83, v2
	v_mov_b32_e32 v84, v2
	v_mov_b32_e32 v85, v2
	v_mov_b32_e32 v86, v2
	v_mov_b32_e32 v87, v2
	v_mov_b32_e32 v88, v2
	v_mov_b32_e32 v89, v2
	v_mov_b32_e32 v90, v2
	v_mov_b32_e32 v91, v2
	v_mov_b32_e32 v92, v2
	v_mov_b32_e32 v93, v2
	v_mov_b32_e32 v94, v2
	v_mov_b32_e32 v95, v2
	v_mov_b32_e32 v96, v2
	v_mov_b32_e32 v97, v2
	v_mov_b32_e32 v98, v2
	v_mov_b32_e32 v99, v2
	v_mov_b32_e32 v100, v2
	v_mov_b32_e32 v101, v2
	v_mov_b32_e32 v102, v2
	v_mov_b32_e32 v103, v2
	v_mov_b32_e32 v104, v2
	v_mov_b32_e32 v105, v2
	v_mov_b32_e32 v106, v2
	v_mov_b32_e32 v107, v2
	v_mov_b32_e32 v108, v2
	v_mov_b32_e32 v109, v2
	v_mov_b32_e32 v110, v2
	v_mov_b32_e32 v111, v2
	v_mov_b32_e32 v112, v2
	v_mov_b32_e32 v113, v2
	v_mov_b32_e32 v114, v2
	v_mov_b32_e32 v115, v2
	v_mov_b32_e32 v116, v2
	v_mov_b32_e32 v117, v2
	v_mov_b32_e32 v118, v2
	v_mov_b32_e32 v119, v2
	v_mov_b32_e32 v120, v2
	v_mov_b32_e32 v121, v2
	v_mov_b32_e32 v122, v2
	v_mov_b32_e32 v123, v2
	v_mov_b32_e32 v124, v2
	v_mov_b32_e32 v125, v2
	v_mov_b32_e32 v126, v2
	v_mov_b32_e32 v127, v2
	v_mov_b32_e32 v128, v2
	v_mov_b32_e32 v129, v2
	v_readlane_b32 s54, v253, 42
	v_readlane_b32 s55, v253, 43
	v_readlane_b32 s56, v253, 44
	v_readlane_b32 s57, v253, 45
	v_readlane_b32 s58, v253, 46
	v_readlane_b32 s59, v253, 47
	v_readlane_b32 s60, v253, 48
	v_readlane_b32 s61, v253, 49
	v_readlane_b32 s62, v253, 50
	v_readlane_b32 s63, v253, 51
	v_readlane_b32 s64, v253, 52
	v_readlane_b32 s65, v253, 53
	v_readlane_b32 s66, v253, 54
	v_readlane_b32 s67, v253, 55
	s_waitcnt lgkmcnt(0)
	s_barrier
	v_readfirstlane_b32 s100, v138
	v_readfirstlane_b32 s101, v139
	s_nop 0
	s_sub_u32 s100, s100, 0x80
	s_subb_u32 s101, s101, 0
	v_add_u32_e32 v176, s24, v130
	v_subrev_u32_e32 v176, s100, v176
	v_add_u32_e32 v177, s84, v130
	v_subrev_u32_e32 v177, s100, v177
	v_add_u32_e32 v178, s28, v130
	v_subrev_u32_e32 v178, s100, v178
	v_add_u32_e32 v179, s18, v130
	v_subrev_u32_e32 v179, s100, v179
	v_subrev_u32_e32 v180, s100, v138
	v_subrev_u32_e32 v181, s100, v136
	v_subrev_u32_e32 v182, s100, v134
	v_subrev_u32_e32 v183, s100, v132
.LBB0_565:
	s_and_b32 s6, s5, 0x10000
	s_add_i32 s7, s6, 0
	v_add_u32_e32 v190, s7, v146
	v_add_u32_e32 v164, v190, v145
	v_add_u32_e32 v163, s7, v147
	ds_read_b128 v[148:151], v164 offset:32768
	ds_read_b128 v[152:155], v164 offset:34816
	ds_read_b128 v[156:159], v164 offset:36864
	ds_read_b128 v[164:167], v164 offset:38912
	v_add_u32_e32 v202, v163, v145
	ds_read_b128 v[168:171], v202
	ds_read_b128 v[172:175], v202 offset:2048
	s_xor_b32 s6, s6, 0x10000
	s_waitcnt lgkmcnt(1)
	v_mfma_f32_16x16x32_bf16 v[126:129], v[148:151], v[168:171], v[126:129]
	v_mfma_f32_16x16x32_bf16 v[122:125], v[152:155], v[168:171], v[122:125]
	v_mfma_f32_16x16x32_bf16 v[118:121], v[156:159], v[168:171], v[118:121]
	v_mfma_f32_16x16x32_bf16 v[114:117], v[164:167], v[168:171], v[114:117]
	ds_read_b128 v[168:171], v202 offset:4096
	s_waitcnt lgkmcnt(1)
	v_mfma_f32_16x16x32_bf16 v[110:113], v[148:151], v[172:175], v[110:113]
	v_mfma_f32_16x16x32_bf16 v[106:109], v[152:155], v[172:175], v[106:109]
	v_mfma_f32_16x16x32_bf16 v[102:105], v[156:159], v[172:175], v[102:105]
	v_mfma_f32_16x16x32_bf16 v[98:101], v[164:167], v[172:175], v[98:101]
	ds_read_b128 v[172:175], v202 offset:6144
	s_waitcnt lgkmcnt(1)
	v_mfma_f32_16x16x32_bf16 v[94:97], v[148:151], v[168:171], v[94:97]
	v_mfma_f32_16x16x32_bf16 v[90:93], v[152:155], v[168:171], v[90:93]
	v_mfma_f32_16x16x32_bf16 v[86:89], v[156:159], v[168:171], v[86:89]
	v_mfma_f32_16x16x32_bf16 v[82:85], v[164:167], v[168:171], v[82:85]
	ds_read_b128 v[168:171], v202 offset:8192
	s_waitcnt lgkmcnt(1)
	v_mfma_f32_16x16x32_bf16 v[78:81], v[148:151], v[172:175], v[78:81]
	v_mfma_f32_16x16x32_bf16 v[74:77], v[152:155], v[172:175], v[74:77]
	v_mfma_f32_16x16x32_bf16 v[70:73], v[156:159], v[172:175], v[70:73]
	v_mfma_f32_16x16x32_bf16 v[66:69], v[164:167], v[172:175], v[66:69]
	ds_read_b128 v[172:175], v202 offset:10240
	s_waitcnt lgkmcnt(1)
	v_mfma_f32_16x16x32_bf16 v[62:65], v[148:151], v[168:171], v[62:65]
	v_mfma_f32_16x16x32_bf16 v[58:61], v[152:155], v[168:171], v[58:61]
	v_mfma_f32_16x16x32_bf16 v[54:57], v[156:159], v[168:171], v[54:57]
	v_mfma_f32_16x16x32_bf16 v[50:53], v[164:167], v[168:171], v[50:53]
	ds_read_b128 v[168:171], v202 offset:12288
	s_waitcnt lgkmcnt(1)
	v_mfma_f32_16x16x32_bf16 v[46:49], v[148:151], v[172:175], v[46:49]
	v_mfma_f32_16x16x32_bf16 v[42:45], v[152:155], v[172:175], v[42:45]
	v_mfma_f32_16x16x32_bf16 v[38:41], v[156:159], v[172:175], v[38:41]
	v_mfma_f32_16x16x32_bf16 v[34:37], v[164:167], v[172:175], v[34:37]
	ds_read_b128 v[172:175], v202 offset:14336
	s_waitcnt lgkmcnt(1)
	v_mfma_f32_16x16x32_bf16 v[30:33], v[148:151], v[168:171], v[30:33]
	v_mfma_f32_16x16x32_bf16 v[26:29], v[152:155], v[168:171], v[26:29]
	v_mfma_f32_16x16x32_bf16 v[22:25], v[156:159], v[168:171], v[22:25]
	v_mfma_f32_16x16x32_bf16 v[18:21], v[164:167], v[168:171], v[18:21]
	s_waitcnt lgkmcnt(0)
	v_mfma_f32_16x16x32_bf16 v[14:17], v[148:151], v[172:175], v[14:17]
	v_mfma_f32_16x16x32_bf16 v[10:13], v[152:155], v[172:175], v[10:13]
	v_mfma_f32_16x16x32_bf16 v[6:9], v[156:159], v[172:175], v[6:9]
	v_mfma_f32_16x16x32_bf16 v[2:5], v[164:167], v[172:175], v[2:5]
	v_readfirstlane_b32 s7, v144
	s_nop 0
	s_add_u32 s7, s7, s6
	s_add_u32 m0, s7, 0x0
	s_nop 0
	global_load_lds_dwordx4 v176, s[100:101]
	s_add_u32 m0, s7, 0x2000
	s_nop 0
	global_load_lds_dwordx4 v177, s[100:101]
	s_add_u32 m0, s7, 0x4000
	s_nop 0
	global_load_lds_dwordx4 v178, s[100:101]
	s_add_u32 m0, s7, 0x6000
	s_nop 0
	global_load_lds_dwordx4 v179, s[100:101]
	s_add_u32 m0, s7, 0x8000
	s_nop 0
	global_load_lds_dwordx4 v180, s[100:101]
	s_add_u32 m0, s7, 0xa000
	s_nop 0
	global_load_lds_dwordx4 v181, s[100:101]
	s_add_u32 m0, s7, 0xc000
	s_nop 0
	global_load_lds_dwordx4 v182, s[100:101]
	s_add_u32 m0, s7, 0xe000
	s_nop 0
	global_load_lds_dwordx4 v183, s[100:101]
	v_add_u32_e32 v160, v190, v143
	ds_read_b128 v[148:151], v160 offset:32768
	ds_read_b128 v[152:155], v160 offset:34816
	ds_read_b128 v[156:159], v160 offset:36864
	ds_read_b128 v[164:167], v160 offset:38912
	v_add_u32_e32 v160, v163, v143
	ds_read_b128 v[168:171], v160
	ds_read_b128 v[172:175], v160 offset:2048
	s_waitcnt lgkmcnt(0)
; #define MFMA16(a, b, c) __builtin_amdgcn_mfma_f32_16x16x32_bf16((a), (b), (c), 0, 0, 0)
;     ...
;   for (int kt = 0; kt < nk; ++kt) {
;     const int buf = kt & 1;
;     const char* cA = smem + buf * STAGE + (wm * 32 * MI + r16) * 128;
;     const char* cB = smem + buf * STAGE + 32768 + (wn * 64 + r16) * 128;
; #pragma unroll
;     for (int k2 = 0; k2 < 2; ++k2) {
;       if (k2 == 1 && kt + 1 < nk) STAGE_TILE(buf ^ 1, (kt + 1) * 64)
;       const int po = ((4 * k2 + q4) ^ swz) * 16;
;       bf16x8 bf[4];
; #pragma unroll
;       for (int nt = 0; nt < 4; ++nt) bf[nt] = *(const bf16x8*)(cB + nt * 16 * 128 + po);
;       bf16x8 afc = *(const bf16x8*)(cA + po);
; #pragma unroll
;       for (int a = 0; a < MT; ++a) {
;         bf16x8 afn = afc;
;         if (a + 1 < MT) afn = *(const bf16x8*)(cA + (a + 1) * 16 * 128 + po);
;         __builtin_amdgcn_sched_barrier(0);
; #pragma unroll
;         for (int nt = 0; nt < 4; ++nt) acc[a][nt] = MFMA16(bf[nt], afc, acc[a][nt]);
;         __builtin_amdgcn_sched_barrier(0);
;         afc = afn;
;       }
;     }
;     asm volatile("s_waitcnt vmcnt(0)" ::: "memory");
;     __syncthreads();
;   }
	v_mfma_f32_16x16x32_bf16 v[126:129], v[148:151], v[168:171], v[126:129]
	v_mfma_f32_16x16x32_bf16 v[122:125], v[152:155], v[168:171], v[122:125]
	v_mfma_f32_16x16x32_bf16 v[118:121], v[156:159], v[168:171], v[118:121]
	v_mfma_f32_16x16x32_bf16 v[114:117], v[164:167], v[168:171], v[114:117]
	ds_read_b128 v[168:171], v160 offset:4096
	v_mfma_f32_16x16x32_bf16 v[110:113], v[148:151], v[172:175], v[110:113]
	v_mfma_f32_16x16x32_bf16 v[106:109], v[152:155], v[172:175], v[106:109]
	v_mfma_f32_16x16x32_bf16 v[102:105], v[156:159], v[172:175], v[102:105]
	v_mfma_f32_16x16x32_bf16 v[98:101], v[164:167], v[172:175], v[98:101]
	ds_read_b128 v[172:175], v160 offset:6144
	s_waitcnt lgkmcnt(0)
	v_mfma_f32_16x16x32_bf16 v[94:97], v[148:151], v[168:171], v[94:97]
	v_mfma_f32_16x16x32_bf16 v[90:93], v[152:155], v[168:171], v[90:93]
	v_mfma_f32_16x16x32_bf16 v[86:89], v[156:159], v[168:171], v[86:89]
	v_mfma_f32_16x16x32_bf16 v[82:85], v[164:167], v[168:171], v[82:85]
	ds_read_b128 v[168:171], v160 offset:8192
	v_mfma_f32_16x16x32_bf16 v[78:81], v[148:151], v[172:175], v[78:81]
	v_mfma_f32_16x16x32_bf16 v[74:77], v[152:155], v[172:175], v[74:77]
	v_mfma_f32_16x16x32_bf16 v[70:73], v[156:159], v[172:175], v[70:73]
	v_mfma_f32_16x16x32_bf16 v[66:69], v[164:167], v[172:175], v[66:69]
	ds_read_b128 v[172:175], v160 offset:10240
	s_waitcnt lgkmcnt(0)
	v_mfma_f32_16x16x32_bf16 v[62:65], v[148:151], v[168:171], v[62:65]
	v_mfma_f32_16x16x32_bf16 v[58:61], v[152:155], v[168:171], v[58:61]
	v_mfma_f32_16x16x32_bf16 v[54:57], v[156:159], v[168:171], v[54:57]
	v_mfma_f32_16x16x32_bf16 v[50:53], v[164:167], v[168:171], v[50:53]
	ds_read_b128 v[168:171], v160 offset:12288
	v_mfma_f32_16x16x32_bf16 v[46:49], v[148:151], v[172:175], v[46:49]
	v_mfma_f32_16x16x32_bf16 v[42:45], v[152:155], v[172:175], v[42:45]
	v_mfma_f32_16x16x32_bf16 v[38:41], v[156:159], v[172:175], v[38:41]
	v_mfma_f32_16x16x32_bf16 v[34:37], v[164:167], v[172:175], v[34:37]
	ds_read_b128 v[172:175], v160 offset:14336
	s_waitcnt lgkmcnt(0)
	v_mfma_f32_16x16x32_bf16 v[30:33], v[148:151], v[168:171], v[30:33]
	v_mfma_f32_16x16x32_bf16 v[26:29], v[152:155], v[168:171], v[26:29]
	v_mfma_f32_16x16x32_bf16 v[22:25], v[156:159], v[168:171], v[22:25]
	v_mfma_f32_16x16x32_bf16 v[18:21], v[164:167], v[168:171], v[18:21]
	v_mfma_f32_16x16x32_bf16 v[14:17], v[148:151], v[172:175], v[14:17]
	v_mfma_f32_16x16x32_bf16 v[10:13], v[152:155], v[172:175], v[10:13]
	v_mfma_f32_16x16x32_bf16 v[6:9], v[156:159], v[172:175], v[6:9]
	v_mfma_f32_16x16x32_bf16 v[2:5], v[164:167], v[172:175], v[2:5]
	s_waitcnt vmcnt(0)
	s_add_u32 s100, s100, 0x80
	s_addc_u32 s101, s101, 0
	s_add_u32 s2, s2, 0x80
	s_addc_u32 s3, s3, 0
	s_add_i32 s5, s5, 0x10000
	s_cmpk_eq_i32 s2, 0x780
	s_waitcnt vmcnt(0)
	s_barrier
	s_cbranch_scc0 .LBB0_565
	s_add_i32 s2, 0, 0x10000
	v_add_u32_e32 v138, s2, v147
	v_readlane_b32 s2, v254, 18
	s_nop 1
	v_add_u32_e32 v139, s2, v146
	v_add_u32_e32 v144, v139, v145
	ds_read_b128 v[130:133], v144
	ds_read_b128 v[134:137], v144 offset:2048
	ds_read_b128 v[146:149], v144 offset:4096
	ds_read_b128 v[150:153], v144 offset:6144
	v_add_u32_e32 v144, v138, v145
	ds_read_b128 v[154:157], v144
	ds_read_b128 v[158:161], v144 offset:2048
	s_waitcnt lgkmcnt(1)
	v_mfma_f32_16x16x32_bf16 v[122:125], v[134:137], v[154:157], v[122:125]
	v_mfma_f32_16x16x32_bf16 v[118:121], v[146:149], v[154:157], v[118:121]
	v_mfma_f32_16x16x32_bf16 v[114:117], v[150:153], v[154:157], v[114:117]
	v_mfma_f32_16x16x32_bf16 v[126:129], v[130:133], v[154:157], v[126:129]
	ds_read_b128 v[154:157], v144 offset:4096
	s_waitcnt lgkmcnt(1)
	v_mfma_f32_16x16x32_bf16 v[110:113], v[130:133], v[158:161], v[110:113]
	v_mfma_f32_16x16x32_bf16 v[106:109], v[134:137], v[158:161], v[106:109]
	v_mfma_f32_16x16x32_bf16 v[102:105], v[146:149], v[158:161], v[102:105]
	v_mfma_f32_16x16x32_bf16 v[98:101], v[150:153], v[158:161], v[98:101]
	ds_read_b128 v[158:161], v144 offset:6144
	s_waitcnt lgkmcnt(1)
	v_mfma_f32_16x16x32_bf16 v[94:97], v[130:133], v[154:157], v[94:97]
	v_mfma_f32_16x16x32_bf16 v[90:93], v[134:137], v[154:157], v[90:93]
	v_mfma_f32_16x16x32_bf16 v[86:89], v[146:149], v[154:157], v[86:89]
	v_mfma_f32_16x16x32_bf16 v[82:85], v[150:153], v[154:157], v[82:85]
	ds_read_b128 v[154:157], v144 offset:8192
	s_waitcnt lgkmcnt(1)
	v_mfma_f32_16x16x32_bf16 v[78:81], v[130:133], v[158:161], v[78:81]
	v_mfma_f32_16x16x32_bf16 v[74:77], v[134:137], v[158:161], v[74:77]
	v_mfma_f32_16x16x32_bf16 v[70:73], v[146:149], v[158:161], v[70:73]
	v_mfma_f32_16x16x32_bf16 v[66:69], v[150:153], v[158:161], v[66:69]
	ds_read_b128 v[158:161], v144 offset:10240
	s_waitcnt lgkmcnt(1)
	v_mfma_f32_16x16x32_bf16 v[62:65], v[130:133], v[154:157], v[62:65]
	v_mfma_f32_16x16x32_bf16 v[58:61], v[134:137], v[154:157], v[58:61]
	v_mfma_f32_16x16x32_bf16 v[54:57], v[146:149], v[154:157], v[54:57]
	v_mfma_f32_16x16x32_bf16 v[50:53], v[150:153], v[154:157], v[50:53]
	ds_read_b128 v[154:157], v144 offset:12288
	s_waitcnt lgkmcnt(1)
	v_mfma_f32_16x16x32_bf16 v[46:49], v[130:133], v[158:161], v[46:49]
	v_mfma_f32_16x16x32_bf16 v[42:45], v[134:137], v[158:161], v[42:45]
	v_mfma_f32_16x16x32_bf16 v[38:41], v[146:149], v[158:161], v[38:41]
	v_mfma_f32_16x16x32_bf16 v[34:37], v[150:153], v[158:161], v[34:37]
	ds_read_b128 v[158:161], v144 offset:14336
	s_waitcnt lgkmcnt(1)
	v_mfma_f32_16x16x32_bf16 v[30:33], v[130:133], v[154:157], v[30:33]
	v_mfma_f32_16x16x32_bf16 v[26:29], v[134:137], v[154:157], v[26:29]
	v_mfma_f32_16x16x32_bf16 v[22:25], v[146:149], v[154:157], v[22:25]
	v_mfma_f32_16x16x32_bf16 v[18:21], v[150:153], v[154:157], v[18:21]
	s_waitcnt lgkmcnt(0)
; #define MFMA16(a, b, c) __builtin_amdgcn_mfma_f32_16x16x32_bf16((a), (b), (c), 0, 0, 0)
; DI bf16_t f2bf(float x) { return (bf16_t)(pack2(x, 0.f) & 0xffffu); }
;     ...
; #pragma unroll
;     for (int k2 = 0; k2 < 2; ++k2) {
;       if (k2 == 1 && kt + 1 < nk) STAGE_TILE(buf ^ 1, (kt + 1) * 64)
;       const int po = ((4 * k2 + q4) ^ swz) * 16;
;       bf16x8 bf[4];
; #pragma unroll
;       for (int nt = 0; nt < 4; ++nt) bf[nt] = *(const bf16x8*)(cB + nt * 16 * 128 + po);
;       bf16x8 afc = *(const bf16x8*)(cA + po);
; #pragma unroll
;       for (int a = 0; a < MT; ++a) {
;         bf16x8 afn = afc;
;         if (a + 1 < MT) afn = *(const bf16x8*)(cA + (a + 1) * 16 * 128 + po);
;         __builtin_amdgcn_sched_barrier(0);
; #pragma unroll
;         for (int nt = 0; nt < 4; ++nt) acc[a][nt] = MFMA16(bf[nt], afc, acc[a][nt]);
;         __builtin_amdgcn_sched_barrier(0);
;         afc = afn;
;       }
; DI void phase_win(char* smem, const Params& p, int layer) {
;     ...
;     if (cbw > 2432) return;
;     const int b = row / TT, t = row - b * TT;
;     const bool lat = t >= CTXL;
;     const int pos = t - CTXL;
;     float v[16] = {c0[0], c0[1], c0[2], c0[3], c1[0], c1[1], c1[2], c1[3], c2[0], c2[1], c2[2], c2[3], c3[0], c3[1], c3[2], c3[3]};
;     if (cbw >= 640 && cbw < 768) {
;       bf16_t* vp = p.VsT + ((size_t)(b * 2 + ((cbw - 640) >> 6)) * 64 + q4 * 16) * TT + t;
; #pragma unroll
;       for (int i = 0; i < 16; ++i) vp[(size_t)i * TT] = f2bf(v[i]);
;       return;
;     }
;     const bool r16 = cbw >= 256 && cbw < 640, rkr = cbw == 2432;
;     if (rkr && q4 >= 2) return;
	v_mfma_f32_16x16x32_bf16 v[14:17], v[130:133], v[158:161], v[14:17]
	v_mfma_f32_16x16x32_bf16 v[10:13], v[134:137], v[158:161], v[10:13]
	v_mfma_f32_16x16x32_bf16 v[6:9], v[146:149], v[158:161], v[6:9]
	v_mfma_f32_16x16x32_bf16 v[2:5], v[150:153], v[158:161], v[2:5]
	v_add_u32_e32 v130, v139, v143
	ds_read_b128 v[134:137], v130
	ds_read_b128 v[144:147], v130 offset:2048
	ds_read_b128 v[148:151], v130 offset:4096
	ds_read_b128 v[152:155], v130 offset:6144
	v_add_u32_e32 v138, v138, v143
	ds_read_b128 v[156:159], v138
	ds_read_b128 v[164:167], v138 offset:2048
	s_waitcnt lgkmcnt(1)
	v_mfma_f32_16x16x32_bf16 v[130:133], v[134:137], v[156:159], v[126:129]
	v_mfma_f32_16x16x32_bf16 v[122:125], v[144:147], v[156:159], v[122:125]
	v_mfma_f32_16x16x32_bf16 v[118:121], v[148:151], v[156:159], v[118:121]
	v_mfma_f32_16x16x32_bf16 v[114:117], v[152:155], v[156:159], v[114:117]
	ds_read_b128 v[126:129], v138 offset:4096
	s_waitcnt lgkmcnt(1)
	v_mfma_f32_16x16x32_bf16 v[110:113], v[134:137], v[164:167], v[110:113]
	v_mfma_f32_16x16x32_bf16 v[106:109], v[144:147], v[164:167], v[106:109]
	v_mfma_f32_16x16x32_bf16 v[102:105], v[148:151], v[164:167], v[102:105]
	v_mfma_f32_16x16x32_bf16 v[98:101], v[152:155], v[164:167], v[98:101]
	ds_read_b128 v[156:159], v138 offset:6144
	s_waitcnt lgkmcnt(1)
	v_mfma_f32_16x16x32_bf16 v[94:97], v[134:137], v[126:129], v[94:97]
	v_mfma_f32_16x16x32_bf16 v[90:93], v[144:147], v[126:129], v[90:93]
	v_mfma_f32_16x16x32_bf16 v[86:89], v[148:151], v[126:129], v[86:89]
	v_mfma_f32_16x16x32_bf16 v[82:85], v[152:155], v[126:129], v[82:85]
	ds_read_b128 v[126:129], v138 offset:8192
	s_waitcnt lgkmcnt(1)
	v_mfma_f32_16x16x32_bf16 v[78:81], v[134:137], v[156:159], v[78:81]
	v_mfma_f32_16x16x32_bf16 v[74:77], v[144:147], v[156:159], v[74:77]
	v_mfma_f32_16x16x32_bf16 v[70:73], v[148:151], v[156:159], v[70:73]
	v_mfma_f32_16x16x32_bf16 v[66:69], v[152:155], v[156:159], v[66:69]
	ds_read_b128 v[156:159], v138 offset:10240
	s_waitcnt lgkmcnt(1)
	v_mfma_f32_16x16x32_bf16 v[62:65], v[134:137], v[126:129], v[62:65]
	v_mfma_f32_16x16x32_bf16 v[58:61], v[144:147], v[126:129], v[58:61]
	v_mfma_f32_16x16x32_bf16 v[54:57], v[148:151], v[126:129], v[54:57]
	v_mfma_f32_16x16x32_bf16 v[50:53], v[152:155], v[126:129], v[50:53]
	ds_read_b128 v[126:129], v138 offset:12288
	s_waitcnt lgkmcnt(1)
	v_mfma_f32_16x16x32_bf16 v[46:49], v[134:137], v[156:159], v[46:49]
	v_mfma_f32_16x16x32_bf16 v[42:45], v[144:147], v[156:159], v[42:45]
	v_mfma_f32_16x16x32_bf16 v[38:41], v[148:151], v[156:159], v[38:41]
	v_mfma_f32_16x16x32_bf16 v[34:37], v[152:155], v[156:159], v[34:37]
	ds_read_b128 v[156:159], v138 offset:14336
	s_waitcnt lgkmcnt(1)
	v_mfma_f32_16x16x32_bf16 v[30:33], v[134:137], v[126:129], v[30:33]
	v_mfma_f32_16x16x32_bf16 v[26:29], v[144:147], v[126:129], v[26:29]
	v_mfma_f32_16x16x32_bf16 v[22:25], v[148:151], v[126:129], v[22:25]
	v_mfma_f32_16x16x32_bf16 v[18:21], v[152:155], v[126:129], v[18:21]
	s_waitcnt lgkmcnt(0)
	v_mfma_f32_16x16x32_bf16 v[14:17], v[134:137], v[156:159], v[14:17]
	v_mfma_f32_16x16x32_bf16 v[10:13], v[144:147], v[156:159], v[10:13]
	v_mfma_f32_16x16x32_bf16 v[6:9], v[148:151], v[156:159], v[6:9]
	v_mfma_f32_16x16x32_bf16 v[2:5], v[152:155], v[156:159], v[2:5]
	s_waitcnt vmcnt(0)
	v_lshl_or_b32 v190, v142, 6, s22
	s_movk_i32 s2, 0x981
	v_cmp_gt_i32_e32 vcc, s2, v190
	s_barrier
	s_and_saveexec_b64 s[96:97], vcc
	s_cbranch_execz .LBB0_557
	v_or_b32_e32 v126, s4, v162
	v_lshl_add_u32 v136, v141, 7, v126
	v_and_b32_e32 v126, 0xffffff80, v190
	s_movk_i32 s2, 0x280
	v_cmp_ne_u32_e64 s[16:17], s2, v126
	s_movk_i32 s2, 0x27f
	v_cmp_lt_i32_e64 s[4:5], s2, v190
	s_movk_i32 s2, 0x980
	v_cmp_ne_u32_e64 s[8:9], s2, v190
	v_cmp_gt_u32_e64 s[6:7], 2, v140
	v_add_u32_e32 v126, 0xffffff00, v190
	v_cmp_eq_u32_e32 vcc, s2, v190
	s_or_b64 s[2:3], s[8:9], s[6:7]
	s_movk_i32 s6, 0x180
	v_cmp_gt_u32_e64 s[12:13], s6, v126
	s_or_b64 s[86:87], vcc, s[12:13]
	v_lshrrev_b32_e32 v160, 6, v126
	v_cndmask_b32_e64 v127, 0, 1, s[12:13]
	v_lshrrev_b32_e32 v127, v127, v140
	v_cmp_eq_u32_e64 s[14:15], 0, v127
	v_add_u32_e32 v127, 0xfffffe00, v190
	v_mul_hi_i32 v126, v136, s1
	s_cmp_eq_u32 s10, 1
	v_lshrrev_b32_e32 v159, 6, v127
	v_lshrrev_b32_e32 v127, 31, v126
	v_ashrrev_i32_e32 v126, 11, v126
	v_lshlrev_b32_e32 v158, 4, v140
	s_movk_i32 s6, 0x1ff
	s_cselect_b64 s[94:95], -1, 0
	s_movk_i32 s10, 0xff
	s_cmpk_gt_u32 s22, 0x7ff
	v_add_u32_e32 v139, v126, v127
	v_and_b32_e32 v161, 16, v158
	v_cmp_lt_i32_e64 s[6:7], s6, v190
	v_cmp_lt_i32_e64 s[10:11], s10, v190
	s_cselect_b64 s[22:23], -1, 0
	v_ashrrev_i32_e32 v135, 31, v190
	v_mov_b32_e32 v134, v190
	v_mad_i32_i24 v138, v139, s80, v136
	s_and_saveexec_b64 s[30:31], s[16:17]
	s_xor_b64 s[30:31], exec, s[30:31]
	s_cbranch_execz .LBB0_594
; DI void phase_win(char* smem, const Params& p, int layer) {
;     ...
;     if (lat && (r16 || rkr)) {
;       const int a = r16 ? (q4 >> 1) : q4;
;       const int pa = a ? (pos & 63) : (pos >> 6);
;       const float* tab = r16 ? p.ropeS + 2 * (pa * 16 + (q4 & 1) * 8) : p.ropeM + 2 * (pa * 8);
; #pragma unroll
;       for (int k = 0; k < 4; ++k) {
;         const float4 cs = *(const float4*)(tab + 4 * k);
;         const float x0 = v[4 * k], x1 = v[4 * k + 1], x2 = v[4 * k + 2], x3 = v[4 * k + 3];
;         v[4 * k] = x0 * cs.x - x1 * cs.y; v[4 * k + 1] = x1 * cs.x + x0 * cs.y;
;         v[4 * k + 2] = x2 * cs.z - x3 * cs.w; v[4 * k + 3] = x3 * cs.z + x2 * cs.w;
;       }
;     }
	s_and_saveexec_b64 s[52:53], s[2:3]
	s_cbranch_execz .LBB0_593
	s_movk_i32 s45, 0xff
	v_cmp_lt_i32_e32 vcc, s45, v138
	s_and_b64 s[46:47], s[86:87], vcc
	v_mov_b32_e32 v140, v131
	v_mov_b32_e32 v141, v133
	v_mov_b32_e32 v142, v123
	v_mov_b32_e32 v143, v125
	v_mov_b32_e32 v144, v119
	v_mov_b32_e32 v145, v121
	v_mov_b32_e32 v154, v115
	v_mov_b32_e32 v155, v117
	v_mov_b32_e32 v146, v130
	v_mov_b32_e32 v147, v132
	v_mov_b32_e32 v148, v122
	v_mov_b32_e32 v149, v124
	v_mov_b32_e32 v150, v118
	v_mov_b32_e32 v151, v120
	v_mov_b32_e32 v152, v114
	v_mov_b32_e32 v153, v116
	s_and_saveexec_b64 s[54:55], s[46:47]
	s_cbranch_execz .LBB0_571
	v_readlane_b32 s46, v252, 1
	v_cndmask_b32_e64 v128, v238, v240, s[12:13]
	v_mov_b32_e32 v129, v191
	v_readlane_b32 s47, v252, 2
	v_add_u32_e32 v126, 0xffffff00, v138
	v_lshrrev_b32_e32 v126, 6, v126
	v_lshl_add_u64 v[128:129], s[46:47], 0, v[128:129]
	global_load_dwordx2 v[128:129], v[128:129], off
	v_cndmask_b32_e64 v126, v162, v126, s[14:15]
	v_lshlrev_b32_e32 v127, 4, v126
	v_lshl_or_b32 v126, v126, 5, v161
	v_cndmask_b32_e64 v126, v127, v126, s[12:13]
	v_mov_b32_e32 v127, v191
	v_mov_b32_e32 v182, v130
	v_mov_b32_e32 v183, v133
	v_mov_b32_e32 v130, v131
	v_mov_b32_e32 v131, v132
	s_waitcnt vmcnt(0)
	v_lshl_add_u64 v[156:157], v[126:127], 2, v[128:129]
	global_load_dwordx4 v[126:129], v[156:157], off offset:48
	global_load_dwordx4 v[164:167], v[156:157], off offset:32
	global_load_dwordx4 v[168:171], v[156:157], off offset:16
	global_load_dwordx4 v[172:175], v[156:157], off
	s_waitcnt vmcnt(3)
	v_mov_b32_e32 v156, v127
	s_waitcnt vmcnt(2)
	v_mov_b32_e32 v180, v165
	s_waitcnt vmcnt(1)
	v_mov_b32_e32 v178, v169
	s_waitcnt vmcnt(0)
	v_mov_b32_e32 v132, v172
	v_mov_b32_e32 v133, v175
	v_mov_b32_e32 v176, v173
	v_mov_b32_e32 v177, v174
	v_pk_mul_f32 v[130:131], v[130:131], v[132:133]
	v_mov_b32_e32 v132, v173
	v_pk_mul_f32 v[132:133], v[140:141], v[132:133]
	v_pk_fma_f32 v[140:141], v[182:183], v[176:177], v[130:131]
	v_mov_b32_e32 v130, v122
	v_mov_b32_e32 v131, v125
	v_mov_b32_e32 v122, v123
	v_mov_b32_e32 v123, v124
	v_mov_b32_e32 v124, v168
	v_mov_b32_e32 v125, v171
	v_mov_b32_e32 v179, v170
	v_pk_mul_f32 v[122:123], v[122:123], v[124:125]
	v_mov_b32_e32 v124, v169
	v_pk_mul_f32 v[124:125], v[142:143], v[124:125]
	v_pk_fma_f32 v[142:143], v[130:131], v[178:179], v[122:123]
	v_mov_b32_e32 v122, v118
	v_mov_b32_e32 v123, v121
	v_mov_b32_e32 v118, v119
	v_mov_b32_e32 v119, v120
	v_mov_b32_e32 v120, v164
	v_mov_b32_e32 v121, v167
	v_mov_b32_e32 v181, v166
	v_pk_mul_f32 v[118:119], v[118:119], v[120:121]
	v_mov_b32_e32 v120, v165
	v_pk_mul_f32 v[120:121], v[144:145], v[120:121]
	v_pk_fma_f32 v[144:145], v[122:123], v[180:181], v[118:119]
	v_mov_b32_e32 v118, v114
	v_mov_b32_e32 v119, v117
	v_mov_b32_e32 v114, v115
	v_mov_b32_e32 v115, v116
	v_mov_b32_e32 v116, v126
	v_mov_b32_e32 v117, v129
	v_pk_mul_f32 v[114:115], v[114:115], v[116:117]
	v_mov_b32_e32 v116, v127
	v_mov_b32_e32 v157, v128
	v_mov_b32_e32 v173, v174
	v_mov_b32_e32 v169, v170
	v_mov_b32_e32 v165, v166
	v_pk_mul_f32 v[116:117], v[154:155], v[116:117]
	v_mov_b32_e32 v127, v128
	v_pk_fma_f32 v[146:147], v[146:147], v[172:173], v[132:133] neg_lo:[0,0,1] neg_hi:[0,0,1]
	v_pk_fma_f32 v[148:149], v[148:149], v[168:169], v[124:125] neg_lo:[0,0,1] neg_hi:[0,0,1]
	v_pk_fma_f32 v[150:151], v[150:151], v[164:165], v[120:121] neg_lo:[0,0,1] neg_hi:[0,0,1]
	v_pk_fma_f32 v[152:153], v[152:153], v[126:127], v[116:117] neg_lo:[0,0,1] neg_hi:[0,0,1]
	v_pk_fma_f32 v[154:155], v[118:119], v[156:157], v[114:115]
